# gdn_g1 forward substitution: A-matrix LDS reads software-prefetched 7 reads ahead through a rotating register pool with counted lgkmcnt waits (arithmetic order unchanged)
# speedup vs baseline: 1.0196x; 1.0100x over previous
; DI void gdn_g1(const Params& p, int l, int ch, char* smem) {
;     ...
;   { const float f2 = bc * expf(Gc);
; #pragma unroll
;     for (int d = 0; d < 16; ++d) { sR[c * 129 + part * 16 + d] *= bc; sR[c * 129 + 64 + part * 16 + d] *= f2; } }
;   __syncthreads();
;   if (tid < 128) {
;     float sol[64];
; #pragma unroll
;     for (int cc = 0; cc < 64; ++cc) sol[cc] = sR[cc * 129 + tid];
.LBB0_660:
	s_or_b64 exec, exec, s[8:9]
	v_mul_f32_e32 v5, 0x3fb8aa3b, v2
	ds_write_b32 v6, v8 offset:240
	v_rndne_f32_e32 v6, v5
	s_mov_b32 s2, 0x3fb8aa3b
	v_sub_f32_e32 v7, v5, v6
	v_fma_f32 v5, v2, s2, -v5
	v_fmac_f32_e32 v5, 0x32a5705f, v2
	v_add_f32_e32 v5, v7, v5
	v_exp_f32_e32 v5, v5
	v_cvt_i32_f32_e32 v6, v6
	v_add_u32_e32 v71, 0x4000, v4
	s_waitcnt lgkmcnt(0)
	s_barrier
	v_ldexp_f32 v5, v5, v6
	ds_read2_b32 v[6:7], v71 offset1:1
	v_mov_b32_e32 v8, v3
	s_mov_b32 s2, 0xc2ce8ed0
	v_cmp_ngt_f32_e32 vcc, s2, v2
	s_mov_b32 s2, 0x42b17218
	s_waitcnt lgkmcnt(0)
	v_pk_mul_f32 v[6:7], v[8:9], v[6:7] op_sel_hi:[0,1]
	ds_write2_b32 v71, v6, v7 offset1:1
	ds_read2_b32 v[6:7], v65 offset1:1
	v_cndmask_b32_e32 v5, 0, v5, vcc
	v_cmp_nlt_f32_e32 vcc, s2, v2
	v_add_u32_e32 v72, 0x4008, v4
	v_add_u32_e32 v73, 0x4010, v4
	v_cndmask_b32_e32 v2, v187, v5, vcc
	v_mul_f32_e32 v2, v3, v2
	s_waitcnt lgkmcnt(0)
	v_pk_mul_f32 v[6:7], v[2:3], v[6:7] op_sel_hi:[0,1]
	ds_write2_b32 v65, v6, v7 offset1:1
	ds_read2_b32 v[6:7], v72 offset1:1
	v_add_u32_e32 v74, 0x4018, v4
	v_add_u32_e32 v78, 0x4038, v4
	v_add_u32_e32 v75, 0x4020, v4
	v_add_u32_e32 v76, 0x4028, v4
	s_waitcnt lgkmcnt(0)
	v_pk_mul_f32 v[6:7], v[8:9], v[6:7] op_sel_hi:[0,1]
	ds_write2_b32 v72, v6, v7 offset1:1
	ds_read2_b32 v[6:7], v66 offset1:1
	v_add_u32_e32 v77, 0x4030, v4
	s_movk_i32 s2, 0x80
	v_cmp_gt_i32_e32 vcc, s2, v89
	ds_read2_b32 v[4:5], v78 offset1:1
	s_waitcnt lgkmcnt(1)
	v_pk_mul_f32 v[6:7], v[2:3], v[6:7] op_sel_hi:[0,1]
	ds_write2_b32 v66, v6, v7 offset1:1
	ds_read2_b32 v[6:7], v73 offset1:1
	s_waitcnt lgkmcnt(2)
	v_pk_mul_f32 v[4:5], v[8:9], v[4:5] op_sel_hi:[0,1]
	ds_write2_b32 v78, v4, v5 offset1:1
	ds_read2_b32 v[4:5], v63 offset1:1
	s_waitcnt lgkmcnt(2)
	v_pk_mul_f32 v[6:7], v[8:9], v[6:7] op_sel_hi:[0,1]
	ds_write2_b32 v73, v6, v7 offset1:1
	ds_read2_b32 v[6:7], v70 offset1:1
	s_waitcnt lgkmcnt(0)
	v_pk_mul_f32 v[6:7], v[2:3], v[6:7] op_sel_hi:[0,1]
	ds_write2_b32 v70, v6, v7 offset1:1
	ds_read2_b32 v[6:7], v74 offset1:1
	s_waitcnt lgkmcnt(0)
	v_pk_mul_f32 v[6:7], v[8:9], v[6:7] op_sel_hi:[0,1]
	ds_write2_b32 v74, v6, v7 offset1:1
	ds_read2_b32 v[6:7], v64 offset1:1
	s_waitcnt lgkmcnt(0)
	v_pk_mul_f32 v[6:7], v[2:3], v[6:7] op_sel_hi:[0,1]
	ds_write2_b32 v64, v6, v7 offset1:1
	ds_read2_b32 v[6:7], v75 offset1:1
	s_waitcnt lgkmcnt(0)
	v_pk_mul_f32 v[6:7], v[8:9], v[6:7] op_sel_hi:[0,1]
	ds_write2_b32 v75, v6, v7 offset1:1
	ds_read2_b32 v[6:7], v67 offset1:1
	s_waitcnt lgkmcnt(0)
	v_pk_mul_f32 v[6:7], v[2:3], v[6:7] op_sel_hi:[0,1]
	ds_write2_b32 v67, v6, v7 offset1:1
	ds_read2_b32 v[6:7], v76 offset1:1
	s_waitcnt lgkmcnt(0)
	v_pk_mul_f32 v[6:7], v[8:9], v[6:7] op_sel_hi:[0,1]
	ds_write2_b32 v76, v6, v7 offset1:1
	ds_read2_b32 v[6:7], v69 offset1:1
	s_waitcnt lgkmcnt(0)
	v_pk_mul_f32 v[6:7], v[2:3], v[6:7] op_sel_hi:[0,1]
	ds_write2_b32 v69, v6, v7 offset1:1
	ds_read2_b32 v[6:7], v77 offset1:1
	s_waitcnt lgkmcnt(0)
	v_pk_mul_f32 v[6:7], v[8:9], v[6:7] op_sel_hi:[0,1]
	ds_write2_b32 v77, v6, v7 offset1:1
	ds_read2_b32 v[6:7], v68 offset1:1
	s_waitcnt lgkmcnt(0)
	v_pk_mul_f32 v[6:7], v[2:3], v[6:7] op_sel_hi:[0,1]
	v_pk_mul_f32 v[2:3], v[2:3], v[4:5] op_sel_hi:[0,1]
	ds_write2_b32 v68, v6, v7 offset1:1
	ds_write2_b32 v63, v2, v3 offset1:1
	s_waitcnt lgkmcnt(0)
	s_barrier
	s_and_saveexec_b64 s[44:45], vcc
	s_cbranch_execz .LBB0_662
	v_lshlrev_b32_e32 v79, 2, v89
	v_add_u32_e32 v2, 0x4000, v79
	ds_read2_b32 v[4:5], v2 offset1:129
	v_add_u32_e32 v2, 0x4400, v79
	ds_read2_b32 v[80:81], v2 offset0:2 offset1:131
	v_add_u32_e32 v2, 0x4800, v79
	ds_read2_b32 v[90:91], v2 offset0:4 offset1:133
	v_add_u32_e32 v2, 0x4c00, v79
	ds_read2_b32 v[60:61], v2 offset0:6 offset1:135
	v_add_u32_e32 v2, 0x5000, v79
	ds_read2_b32 v[58:59], v2 offset0:8 offset1:137
	v_add_u32_e32 v2, 0x5400, v79
	ds_read2_b32 v[56:57], v2 offset0:10 offset1:139
	v_add_u32_e32 v2, 0x5800, v79
	ds_read2_b32 v[54:55], v2 offset0:12 offset1:141
	v_add_u32_e32 v2, 0x5c00, v79
	ds_read2_b32 v[52:53], v2 offset0:14 offset1:143
	v_add_u32_e32 v2, 0x6000, v79
	ds_read2_b32 v[50:51], v2 offset0:16 offset1:145
	v_add_u32_e32 v2, 0x6400, v79
	ds_read2_b32 v[48:49], v2 offset0:18 offset1:147
	v_add_u32_e32 v2, 0x6800, v79
	ds_read2_b32 v[46:47], v2 offset0:20 offset1:149
	v_add_u32_e32 v2, 0x6c00, v79
	ds_read2_b32 v[44:45], v2 offset0:22 offset1:151
	v_add_u32_e32 v2, 0x7000, v79
	ds_read2_b32 v[42:43], v2 offset0:24 offset1:153
	v_add_u32_e32 v2, 0x7400, v79
	ds_read2_b32 v[40:41], v2 offset0:26 offset1:155
	v_add_u32_e32 v2, 0x7800, v79
	ds_read2_b32 v[38:39], v2 offset0:28 offset1:157
	v_add_u32_e32 v2, 0x7c00, v79
	ds_read2_b32 v[36:37], v2 offset0:30 offset1:159
	v_add_u32_e32 v2, 0x8000, v79
	ds_read2_b32 v[34:35], v2 offset0:32 offset1:161
	v_add_u32_e32 v2, 0x8400, v79
	ds_read2_b32 v[32:33], v2 offset0:34 offset1:163
	v_add_u32_e32 v2, 0x8800, v79
	ds_read2_b32 v[30:31], v2 offset0:36 offset1:165
	v_add_u32_e32 v2, 0x8c00, v79
	ds_read2_b32 v[28:29], v2 offset0:38 offset1:167
	v_add_u32_e32 v2, 0x9000, v79
	ds_read2_b32 v[26:27], v2 offset0:40 offset1:169
	v_add_u32_e32 v2, 0x9400, v79
	ds_read2_b32 v[24:25], v2 offset0:42 offset1:171
	v_add_u32_e32 v2, 0x9800, v79
	ds_read2_b32 v[22:23], v2 offset0:44 offset1:173
	v_add_u32_e32 v2, 0x9c00, v79
	ds_read2_b32 v[20:21], v2 offset0:46 offset1:175
	v_add_u32_e32 v2, 0xa000, v79
	ds_read2_b32 v[18:19], v2 offset0:48 offset1:177
	v_add_u32_e32 v2, 0xa400, v79
	ds_read2_b32 v[16:17], v2 offset0:50 offset1:179
	v_add_u32_e32 v2, 0xa800, v79
	ds_read2_b32 v[14:15], v2 offset0:52 offset1:181
	v_add_u32_e32 v2, 0xac00, v79
	ds_read2_b32 v[12:13], v2 offset0:54 offset1:183
	v_add_u32_e32 v2, 0xb000, v79
	ds_read2_b32 v[10:11], v2 offset0:56 offset1:185
	v_add_u32_e32 v2, 0xb400, v79
	ds_read2_b32 v[8:9], v2 offset0:58 offset1:187
	v_add_u32_e32 v2, 0xb800, v79
	ds_read2_b32 v[6:7], v2 offset0:60 offset1:189
	v_add_u32_e32 v2, 0xbc00, v79
	ds_read2_b32 v[2:3], v2 offset0:62 offset1:191
	ds_read_b32 v82, v143 offset:256
	s_waitcnt lgkmcnt(0)
; DI void gdn_g1(const Params& p, int l, int ch, char* smem) {
;     ...
;     for (int cc = 1; cc < 64; ++cc) { float a0 = 0.f, a1 = 0.f;
; #pragma unroll
;       for (int s2 = 0; s2 < cc; ++s2) { if (s2 & 1) a1 += sA[cc * 64 + s2] * sol[s2]; else a0 += sA[cc * 64 + s2] * sol[s2]; }
;       sol[cc] -= a0 + a1; }
	v_fma_f32 v82, v4, v82, 0
	v_sub_f32_e32 v5, v5, v82
	ds_read_b64 v[82:83], v143 offset:512
	s_waitcnt lgkmcnt(0)
	v_fma_f32 v82, v4, v82, 0
	v_fma_f32 v83, v83, v5, 0
	v_add_f32_e32 v82, v82, v83
	v_sub_f32_e32 v80, v80, v82
	ds_read_b96 v[82:84], v143 offset:768
	s_waitcnt lgkmcnt(0)
	v_fma_f32 v82, v4, v82, 0
	v_fma_f32 v83, v5, v83, 0
	v_fmac_f32_e32 v82, v84, v80
	v_add_f32_e32 v82, v83, v82
	v_sub_f32_e32 v81, v81, v82
	ds_read_b128 v[82:85], v143 offset:1024
	s_waitcnt lgkmcnt(0)
	v_fma_f32 v82, v4, v82, 0
	v_fma_f32 v83, v5, v83, 0
	v_fmac_f32_e32 v82, v80, v84
	v_fmac_f32_e32 v83, v85, v81
	ds_read_b128 v[114:117], v143 offset:1280
	ds_read_b32 v119, v143 offset:1296
	ds_read_b128 v[122:125], v143 offset:1536
	ds_read_b64 v[126:127], v143 offset:1552
	ds_read_b128 v[130:133], v143 offset:1792
	ds_read_b96 v[134:136], v143 offset:1808
	ds_read_b128 v[146:149], v143 offset:2048
	ds_read_b128 v[150:153], v143 offset:2064
	v_add_f32_e32 v82, v82, v83
	v_sub_f32_e32 v82, v90, v82
	s_waitcnt lgkmcnt(7)
	v_fma_f32 v83, v4, v114, 0
	v_fma_f32 v84, v5, v115, 0
	v_fmac_f32_e32 v83, v80, v116
	v_fmac_f32_e32 v84, v81, v117
	ds_read_b128 v[114:117], v143 offset:2304
	s_waitcnt lgkmcnt(7)
	v_fmac_f32_e32 v83, v119, v82
	v_add_f32_e32 v83, v84, v83
	ds_read_b128 v[118:121], v143 offset:2320
	v_sub_f32_e32 v83, v91, v83
	s_waitcnt lgkmcnt(7)
	v_fma_f32 v88, v4, v122, 0
	v_fma_f32 v90, v5, v123, 0
	v_fmac_f32_e32 v88, v80, v124
	v_fmac_f32_e32 v90, v81, v125
	ds_read_b32 v122, v143 offset:2336
	s_waitcnt lgkmcnt(7)
	v_fmac_f32_e32 v88, v82, v126
	v_fmac_f32_e32 v90, v83, v127
	v_add_f32_e32 v84, v88, v90
	v_sub_f32_e32 v60, v60, v84
	ds_read_b128 v[126:129], v143 offset:2560
	s_waitcnt lgkmcnt(7)
	v_fma_f32 v88, v4, v130, 0
	v_fma_f32 v90, v5, v131, 0
	v_fmac_f32_e32 v88, v80, v132
	v_fmac_f32_e32 v90, v81, v133
	ds_read_b128 v[130:133], v143 offset:2576
	s_waitcnt lgkmcnt(7)
	v_fmac_f32_e32 v88, v82, v134
	v_fmac_f32_e32 v90, v83, v135
	v_fmac_f32_e32 v88, v60, v136
	v_add_f32_e32 v84, v90, v88
	v_sub_f32_e32 v61, v61, v84
	ds_read_b64 v[134:135], v143 offset:2592
	s_waitcnt lgkmcnt(7)
	v_fma_f32 v88, v4, v146, 0
	v_fma_f32 v90, v5, v147, 0
	v_fmac_f32_e32 v88, v80, v148
	v_fmac_f32_e32 v90, v81, v149
	ds_read_b128 v[146:149], v143 offset:2816
	s_waitcnt lgkmcnt(7)
	v_fmac_f32_e32 v88, v82, v150
	v_fmac_f32_e32 v90, v83, v151
	v_fmac_f32_e32 v88, v60, v152
	v_fmac_f32_e32 v90, v61, v153
	v_add_f32_e32 v84, v88, v90
	v_sub_f32_e32 v58, v58, v84
	ds_read_b128 v[150:153], v143 offset:2832
	s_waitcnt lgkmcnt(7)
	v_fma_f32 v88, v4, v114, 0
	v_fma_f32 v90, v5, v115, 0
	v_fmac_f32_e32 v88, v80, v116
	v_fmac_f32_e32 v90, v81, v117
	ds_read_b96 v[114:116], v143 offset:2848
	s_waitcnt lgkmcnt(7)
	v_fmac_f32_e32 v88, v82, v118
	v_fmac_f32_e32 v90, v83, v119
	v_fmac_f32_e32 v88, v60, v120
	v_fmac_f32_e32 v90, v61, v121
	ds_read_b128 v[118:121], v143 offset:3072
	s_waitcnt lgkmcnt(7)
	v_fmac_f32_e32 v88, v58, v122
	v_add_f32_e32 v84, v90, v88
	v_sub_f32_e32 v59, v59, v84
	ds_read_b128 v[122:125], v143 offset:3088
	s_waitcnt lgkmcnt(7)
	v_fma_f32 v88, v4, v126, 0
	v_fma_f32 v90, v5, v127, 0
	v_fmac_f32_e32 v88, v80, v128
	v_fmac_f32_e32 v90, v81, v129
	ds_read_b128 v[126:129], v143 offset:3104
	s_waitcnt lgkmcnt(7)
	v_fmac_f32_e32 v88, v82, v130
	v_fmac_f32_e32 v90, v83, v131
	v_fmac_f32_e32 v88, v60, v132
	v_fmac_f32_e32 v90, v61, v133
	ds_read_b128 v[130:133], v143 offset:3328
	s_waitcnt lgkmcnt(7)
	v_fmac_f32_e32 v88, v58, v134
	v_fmac_f32_e32 v90, v59, v135
	v_add_f32_e32 v84, v88, v90
	v_sub_f32_e32 v56, v56, v84
	ds_read_b128 v[134:137], v143 offset:3344
	s_waitcnt lgkmcnt(7)
	v_fma_f32 v88, v4, v146, 0
	v_fma_f32 v90, v5, v147, 0
	v_fmac_f32_e32 v88, v80, v148
	v_fmac_f32_e32 v90, v81, v149
	ds_read_b128 v[146:149], v143 offset:3360
	s_waitcnt lgkmcnt(7)
	v_fmac_f32_e32 v88, v82, v150
	v_fmac_f32_e32 v90, v83, v151
	v_fmac_f32_e32 v88, v60, v152
	v_fmac_f32_e32 v90, v61, v153
	ds_read_b32 v150, v143 offset:3376
	s_waitcnt lgkmcnt(7)
	v_fmac_f32_e32 v88, v58, v114
	v_fmac_f32_e32 v90, v59, v115
	v_fmac_f32_e32 v88, v56, v116
	v_add_f32_e32 v84, v90, v88
	v_sub_f32_e32 v57, v57, v84
	ds_read_b128 v[114:117], v143 offset:3584
	s_waitcnt lgkmcnt(7)
	v_fma_f32 v88, v4, v118, 0
	v_fma_f32 v90, v5, v119, 0
	v_fmac_f32_e32 v88, v80, v120
	v_fmac_f32_e32 v90, v81, v121
	ds_read_b128 v[118:121], v143 offset:3600
	s_waitcnt lgkmcnt(7)
	v_fmac_f32_e32 v88, v82, v122
	v_fmac_f32_e32 v90, v83, v123
	v_fmac_f32_e32 v88, v60, v124
	v_fmac_f32_e32 v90, v61, v125
	ds_read_b128 v[122:125], v143 offset:3616
	s_waitcnt lgkmcnt(7)
	v_fmac_f32_e32 v88, v58, v126
	v_fmac_f32_e32 v90, v59, v127
	v_fmac_f32_e32 v88, v56, v128
	v_fmac_f32_e32 v90, v57, v129
	v_add_f32_e32 v84, v88, v90
	v_sub_f32_e32 v54, v54, v84
	ds_read_b64 v[126:127], v143 offset:3632
	s_waitcnt lgkmcnt(7)
	v_fma_f32 v88, v4, v130, 0
	v_fma_f32 v90, v5, v131, 0
	v_fmac_f32_e32 v88, v80, v132
	v_fmac_f32_e32 v90, v81, v133
	ds_read_b128 v[130:133], v143 offset:3840
	s_waitcnt lgkmcnt(7)
	v_fmac_f32_e32 v88, v82, v134
	v_fmac_f32_e32 v90, v83, v135
	v_fmac_f32_e32 v88, v60, v136
	v_fmac_f32_e32 v90, v61, v137
	ds_read_b128 v[134:137], v143 offset:3856
	s_waitcnt lgkmcnt(7)
	v_fmac_f32_e32 v88, v58, v146
	v_fmac_f32_e32 v90, v59, v147
	v_fmac_f32_e32 v88, v56, v148
	v_fmac_f32_e32 v90, v57, v149
	ds_read_b128 v[146:149], v143 offset:3872
	s_waitcnt lgkmcnt(7)
	v_fmac_f32_e32 v88, v54, v150
	v_add_f32_e32 v84, v90, v88
	v_sub_f32_e32 v55, v55, v84
	ds_read_b96 v[150:152], v143 offset:3888
	s_waitcnt lgkmcnt(7)
	v_fma_f32 v88, v4, v114, 0
	v_fma_f32 v90, v5, v115, 0
	v_fmac_f32_e32 v88, v80, v116
	v_fmac_f32_e32 v90, v81, v117
	ds_read_b128 v[114:117], v143 offset:4096
	s_waitcnt lgkmcnt(7)
; DI void gdn_g1(const Params& p, int l, int ch, char* smem) {
;     ...
;     for (int cc = 1; cc < 64; ++cc) { float a0 = 0.f, a1 = 0.f;
; #pragma unroll
;       for (int s2 = 0; s2 < cc; ++s2) { if (s2 & 1) a1 += sA[cc * 64 + s2] * sol[s2]; else a0 += sA[cc * 64 + s2] * sol[s2]; }
;       sol[cc] -= a0 + a1; }
	v_fmac_f32_e32 v88, v82, v118
	v_fmac_f32_e32 v90, v83, v119
	v_fmac_f32_e32 v88, v60, v120
	v_fmac_f32_e32 v90, v61, v121
	ds_read_b128 v[118:121], v143 offset:4112
	s_waitcnt lgkmcnt(7)
	v_fmac_f32_e32 v88, v58, v122
	v_fmac_f32_e32 v90, v59, v123
	v_fmac_f32_e32 v88, v56, v124
	v_fmac_f32_e32 v90, v57, v125
	ds_read_b128 v[122:125], v143 offset:4128
	s_waitcnt lgkmcnt(7)
	v_fmac_f32_e32 v88, v54, v126
	v_fmac_f32_e32 v90, v55, v127
	v_add_f32_e32 v84, v88, v90
	v_sub_f32_e32 v52, v52, v84
	ds_read_b128 v[126:129], v143 offset:4144
	s_waitcnt lgkmcnt(7)
	v_fma_f32 v88, v4, v130, 0
	v_fma_f32 v90, v5, v131, 0
	v_fmac_f32_e32 v88, v80, v132
	v_fmac_f32_e32 v90, v81, v133
	ds_read_b128 v[130:133], v143 offset:4352
	s_waitcnt lgkmcnt(7)
	v_fmac_f32_e32 v88, v82, v134
	v_fmac_f32_e32 v90, v83, v135
	v_fmac_f32_e32 v88, v60, v136
	v_fmac_f32_e32 v90, v61, v137
	ds_read_b128 v[134:137], v143 offset:4368
	s_waitcnt lgkmcnt(7)
	v_fmac_f32_e32 v88, v58, v146
	v_fmac_f32_e32 v90, v59, v147
	v_fmac_f32_e32 v88, v56, v148
	v_fmac_f32_e32 v90, v57, v149
	ds_read_b128 v[146:149], v143 offset:4384
	s_waitcnt lgkmcnt(7)
	v_fmac_f32_e32 v88, v54, v150
	v_fmac_f32_e32 v90, v55, v151
	v_fmac_f32_e32 v88, v52, v152
	v_add_f32_e32 v84, v90, v88
	v_sub_f32_e32 v53, v53, v84
	ds_read_b128 v[150:153], v143 offset:4400
	s_waitcnt lgkmcnt(7)
	v_fma_f32 v88, v4, v114, 0
	v_fma_f32 v90, v5, v115, 0
	v_fmac_f32_e32 v88, v80, v116
	v_fmac_f32_e32 v90, v81, v117
	ds_read_b32 v114, v143 offset:4416
	s_waitcnt lgkmcnt(7)
	v_fmac_f32_e32 v88, v82, v118
	v_fmac_f32_e32 v90, v83, v119
	v_fmac_f32_e32 v88, v60, v120
	v_fmac_f32_e32 v90, v61, v121
	ds_read_b128 v[118:121], v143 offset:4608
	s_waitcnt lgkmcnt(7)
	v_fmac_f32_e32 v88, v58, v122
	v_fmac_f32_e32 v90, v59, v123
	v_fmac_f32_e32 v88, v56, v124
	v_fmac_f32_e32 v90, v57, v125
	ds_read_b128 v[122:125], v143 offset:4624
	s_waitcnt lgkmcnt(7)
	v_fmac_f32_e32 v88, v54, v126
	v_fmac_f32_e32 v90, v55, v127
	v_fmac_f32_e32 v88, v52, v128
	v_fmac_f32_e32 v90, v53, v129
	v_add_f32_e32 v84, v88, v90
	v_sub_f32_e32 v50, v50, v84
	ds_read_b128 v[126:129], v143 offset:4640
	s_waitcnt lgkmcnt(7)
	v_fma_f32 v88, v4, v130, 0
	v_fma_f32 v90, v5, v131, 0
	v_fmac_f32_e32 v88, v80, v132
	v_fmac_f32_e32 v90, v81, v133
	ds_read_b128 v[130:133], v143 offset:4656
	s_waitcnt lgkmcnt(7)
	v_fmac_f32_e32 v88, v82, v134
	v_fmac_f32_e32 v90, v83, v135
	v_fmac_f32_e32 v88, v60, v136
	v_fmac_f32_e32 v90, v61, v137
	ds_read_b64 v[134:135], v143 offset:4672
	s_waitcnt lgkmcnt(7)
	v_fmac_f32_e32 v88, v58, v146
	v_fmac_f32_e32 v90, v59, v147
	v_fmac_f32_e32 v88, v56, v148
	v_fmac_f32_e32 v90, v57, v149
	ds_read_b128 v[146:149], v143 offset:4864
	s_waitcnt lgkmcnt(7)
	v_fmac_f32_e32 v88, v54, v150
	v_fmac_f32_e32 v90, v55, v151
	v_fmac_f32_e32 v88, v52, v152
	v_fmac_f32_e32 v90, v53, v153
	ds_read_b128 v[150:153], v143 offset:4880
	s_waitcnt lgkmcnt(7)
	v_fmac_f32_e32 v88, v50, v114
	v_add_f32_e32 v84, v90, v88
	v_sub_f32_e32 v51, v51, v84
	ds_read_b128 v[114:117], v143 offset:4896
	s_waitcnt lgkmcnt(7)
	v_fma_f32 v88, v4, v118, 0
	v_fma_f32 v90, v5, v119, 0
	v_fmac_f32_e32 v88, v80, v120
	v_fmac_f32_e32 v90, v81, v121
	ds_read_b128 v[118:121], v143 offset:4912
	s_waitcnt lgkmcnt(7)
	v_fmac_f32_e32 v88, v82, v122
	v_fmac_f32_e32 v90, v83, v123
	v_fmac_f32_e32 v88, v60, v124
	v_fmac_f32_e32 v90, v61, v125
	ds_read_b96 v[122:124], v143 offset:4928
	s_waitcnt lgkmcnt(7)
	v_fmac_f32_e32 v88, v58, v126
	v_fmac_f32_e32 v90, v59, v127
	v_fmac_f32_e32 v88, v56, v128
	v_fmac_f32_e32 v90, v57, v129
	ds_read_b128 v[126:129], v143 offset:5120
	s_waitcnt lgkmcnt(7)
	v_fmac_f32_e32 v88, v54, v130
	v_fmac_f32_e32 v90, v55, v131
	v_fmac_f32_e32 v88, v52, v132
	v_fmac_f32_e32 v90, v53, v133
	ds_read_b128 v[130:133], v143 offset:5136
	s_waitcnt lgkmcnt(7)
	v_fmac_f32_e32 v88, v50, v134
	v_fmac_f32_e32 v90, v51, v135
	v_add_f32_e32 v84, v88, v90
	v_sub_f32_e32 v48, v48, v84
	ds_read_b128 v[134:137], v143 offset:5152
	s_waitcnt lgkmcnt(7)
	v_fma_f32 v88, v4, v146, 0
	v_fma_f32 v90, v5, v147, 0
	v_fmac_f32_e32 v88, v80, v148
	v_fmac_f32_e32 v90, v81, v149
	ds_read_b128 v[146:149], v143 offset:5168
	s_waitcnt lgkmcnt(7)
	v_fmac_f32_e32 v88, v82, v150
	v_fmac_f32_e32 v90, v83, v151
	v_fmac_f32_e32 v88, v60, v152
	v_fmac_f32_e32 v90, v61, v153
	ds_read_b128 v[150:153], v143 offset:5184
	s_waitcnt lgkmcnt(7)
	v_fmac_f32_e32 v88, v58, v114
	v_fmac_f32_e32 v90, v59, v115
	v_fmac_f32_e32 v88, v56, v116
	v_fmac_f32_e32 v90, v57, v117
	ds_read_b128 v[114:117], v143 offset:5376
	s_waitcnt lgkmcnt(7)
	v_fmac_f32_e32 v88, v54, v118
	v_fmac_f32_e32 v90, v55, v119
	v_fmac_f32_e32 v88, v52, v120
	v_fmac_f32_e32 v90, v53, v121
	ds_read_b128 v[118:121], v143 offset:5392
	s_waitcnt lgkmcnt(7)
	v_fmac_f32_e32 v88, v50, v122
	v_fmac_f32_e32 v90, v51, v123
	v_fmac_f32_e32 v88, v48, v124
	v_add_f32_e32 v84, v90, v88
	v_sub_f32_e32 v49, v49, v84
	ds_read_b128 v[122:125], v143 offset:5408
	s_waitcnt lgkmcnt(7)
	v_fma_f32 v88, v4, v126, 0
	v_fma_f32 v90, v5, v127, 0
	v_fmac_f32_e32 v88, v80, v128
	v_fmac_f32_e32 v90, v81, v129
	ds_read_b128 v[126:129], v143 offset:5424
	s_waitcnt lgkmcnt(7)
	v_fmac_f32_e32 v88, v82, v130
	v_fmac_f32_e32 v90, v83, v131
	v_fmac_f32_e32 v88, v60, v132
	v_fmac_f32_e32 v90, v61, v133
	ds_read_b128 v[130:133], v143 offset:5440
	s_waitcnt lgkmcnt(7)
	v_fmac_f32_e32 v88, v58, v134
	v_fmac_f32_e32 v90, v59, v135
	v_fmac_f32_e32 v88, v56, v136
	v_fmac_f32_e32 v90, v57, v137
	ds_read_b32 v134, v143 offset:5456
	s_waitcnt lgkmcnt(7)
	v_fmac_f32_e32 v88, v54, v146
	v_fmac_f32_e32 v90, v55, v147
	v_fmac_f32_e32 v88, v52, v148
	v_fmac_f32_e32 v90, v53, v149
	ds_read_b128 v[146:149], v143 offset:5632
	s_waitcnt lgkmcnt(7)
; DI void gdn_g1(const Params& p, int l, int ch, char* smem) {
;     ...
;     for (int cc = 1; cc < 64; ++cc) { float a0 = 0.f, a1 = 0.f;
; #pragma unroll
;       for (int s2 = 0; s2 < cc; ++s2) { if (s2 & 1) a1 += sA[cc * 64 + s2] * sol[s2]; else a0 += sA[cc * 64 + s2] * sol[s2]; }
;       sol[cc] -= a0 + a1; }
	v_fmac_f32_e32 v88, v50, v150
	v_fmac_f32_e32 v90, v51, v151
	v_fmac_f32_e32 v88, v48, v152
	v_fmac_f32_e32 v90, v49, v153
	v_add_f32_e32 v84, v88, v90
	v_sub_f32_e32 v46, v46, v84
	ds_read_b128 v[150:153], v143 offset:5648
	s_waitcnt lgkmcnt(7)
	v_fma_f32 v88, v4, v114, 0
	v_fma_f32 v90, v5, v115, 0
	v_fmac_f32_e32 v88, v80, v116
	v_fmac_f32_e32 v90, v81, v117
	ds_read_b128 v[114:117], v143 offset:5664
	s_waitcnt lgkmcnt(7)
	v_fmac_f32_e32 v88, v82, v118
	v_fmac_f32_e32 v90, v83, v119
	v_fmac_f32_e32 v88, v60, v120
	v_fmac_f32_e32 v90, v61, v121
	ds_read_b128 v[118:121], v143 offset:5680
	s_waitcnt lgkmcnt(7)
	v_fmac_f32_e32 v88, v58, v122
	v_fmac_f32_e32 v90, v59, v123
	v_fmac_f32_e32 v88, v56, v124
	v_fmac_f32_e32 v90, v57, v125
	ds_read_b128 v[122:125], v143 offset:5696
	s_waitcnt lgkmcnt(7)
	v_fmac_f32_e32 v88, v54, v126
	v_fmac_f32_e32 v90, v55, v127
	v_fmac_f32_e32 v88, v52, v128
	v_fmac_f32_e32 v90, v53, v129
	ds_read_b64 v[126:127], v143 offset:5712
	s_waitcnt lgkmcnt(7)
	v_fmac_f32_e32 v88, v50, v130
	v_fmac_f32_e32 v90, v51, v131
	v_fmac_f32_e32 v88, v48, v132
	v_fmac_f32_e32 v90, v49, v133
	ds_read_b128 v[130:133], v143 offset:5888
	s_waitcnt lgkmcnt(7)
	v_fmac_f32_e32 v88, v46, v134
	v_add_f32_e32 v84, v90, v88
	v_sub_f32_e32 v47, v47, v84
	ds_read_b128 v[134:137], v143 offset:5904
	s_waitcnt lgkmcnt(7)
	v_fma_f32 v88, v4, v146, 0
	v_fma_f32 v90, v5, v147, 0
	v_fmac_f32_e32 v88, v80, v148
	v_fmac_f32_e32 v90, v81, v149
	ds_read_b128 v[146:149], v143 offset:5920
	s_waitcnt lgkmcnt(7)
	v_fmac_f32_e32 v88, v82, v150
	v_fmac_f32_e32 v90, v83, v151
	v_fmac_f32_e32 v88, v60, v152
	v_fmac_f32_e32 v90, v61, v153
	ds_read_b128 v[150:153], v143 offset:5936
	s_waitcnt lgkmcnt(7)
	v_fmac_f32_e32 v88, v58, v114
	v_fmac_f32_e32 v90, v59, v115
	v_fmac_f32_e32 v88, v56, v116
	v_fmac_f32_e32 v90, v57, v117
	ds_read_b128 v[114:117], v143 offset:5952
	s_waitcnt lgkmcnt(7)
	v_fmac_f32_e32 v88, v54, v118
	v_fmac_f32_e32 v90, v55, v119
	v_fmac_f32_e32 v88, v52, v120
	v_fmac_f32_e32 v90, v53, v121
	ds_read_b96 v[118:120], v143 offset:5968
	s_waitcnt lgkmcnt(7)
	v_fmac_f32_e32 v88, v50, v122
	v_fmac_f32_e32 v90, v51, v123
	v_fmac_f32_e32 v88, v48, v124
	v_fmac_f32_e32 v90, v49, v125
	ds_read_b128 v[122:125], v143 offset:6144
	s_waitcnt lgkmcnt(7)
	v_fmac_f32_e32 v88, v46, v126
	v_fmac_f32_e32 v90, v47, v127
	v_add_f32_e32 v84, v88, v90
	v_sub_f32_e32 v44, v44, v84
	ds_read_b128 v[126:129], v143 offset:6160
	s_waitcnt lgkmcnt(7)
	v_fma_f32 v88, v4, v130, 0
	v_fma_f32 v90, v5, v131, 0
	v_fmac_f32_e32 v88, v80, v132
	v_fmac_f32_e32 v90, v81, v133
	ds_read_b128 v[130:133], v143 offset:6176
	s_waitcnt lgkmcnt(7)
	v_fmac_f32_e32 v88, v82, v134
	v_fmac_f32_e32 v90, v83, v135
	v_fmac_f32_e32 v88, v60, v136
	v_fmac_f32_e32 v90, v61, v137
	ds_read_b128 v[134:137], v143 offset:6192
	s_waitcnt lgkmcnt(7)
	v_fmac_f32_e32 v88, v58, v146
	v_fmac_f32_e32 v90, v59, v147
	v_fmac_f32_e32 v88, v56, v148
	v_fmac_f32_e32 v90, v57, v149
	ds_read_b128 v[146:149], v143 offset:6208
	s_waitcnt lgkmcnt(7)
	v_fmac_f32_e32 v88, v54, v150
	v_fmac_f32_e32 v90, v55, v151
	v_fmac_f32_e32 v88, v52, v152
	v_fmac_f32_e32 v90, v53, v153
	ds_read_b128 v[150:153], v143 offset:6224
	s_waitcnt lgkmcnt(7)
	v_fmac_f32_e32 v88, v50, v114
	v_fmac_f32_e32 v90, v51, v115
	v_fmac_f32_e32 v88, v48, v116
	v_fmac_f32_e32 v90, v49, v117
	ds_read_b128 v[114:117], v143 offset:6400
	s_waitcnt lgkmcnt(7)
	v_fmac_f32_e32 v88, v46, v118
	v_fmac_f32_e32 v90, v47, v119
	v_fmac_f32_e32 v88, v44, v120
	v_add_f32_e32 v84, v90, v88
	v_sub_f32_e32 v45, v45, v84
	ds_read_b128 v[118:121], v143 offset:6416
	s_waitcnt lgkmcnt(7)
	v_fma_f32 v88, v4, v122, 0
	v_fma_f32 v90, v5, v123, 0
	v_fmac_f32_e32 v88, v80, v124
	v_fmac_f32_e32 v90, v81, v125
	ds_read_b128 v[122:125], v143 offset:6432
	s_waitcnt lgkmcnt(7)
	v_fmac_f32_e32 v88, v82, v126
	v_fmac_f32_e32 v90, v83, v127
	v_fmac_f32_e32 v88, v60, v128
	v_fmac_f32_e32 v90, v61, v129
	ds_read_b128 v[126:129], v143 offset:6448
	s_waitcnt lgkmcnt(7)
	v_fmac_f32_e32 v88, v58, v130
	v_fmac_f32_e32 v90, v59, v131
	v_fmac_f32_e32 v88, v56, v132
	v_fmac_f32_e32 v90, v57, v133
	ds_read_b128 v[130:133], v143 offset:6464
	s_waitcnt lgkmcnt(7)
	v_fmac_f32_e32 v88, v54, v134
	v_fmac_f32_e32 v90, v55, v135
	v_fmac_f32_e32 v88, v52, v136
	v_fmac_f32_e32 v90, v53, v137
	ds_read_b128 v[134:137], v143 offset:6480
	s_waitcnt lgkmcnt(7)
	v_fmac_f32_e32 v88, v50, v146
	v_fmac_f32_e32 v90, v51, v147
	v_fmac_f32_e32 v88, v48, v148
	v_fmac_f32_e32 v90, v49, v149
	ds_read_b32 v146, v143 offset:6496
	s_waitcnt lgkmcnt(7)
	v_fmac_f32_e32 v88, v46, v150
	v_fmac_f32_e32 v90, v47, v151
	v_fmac_f32_e32 v88, v44, v152
	v_fmac_f32_e32 v90, v45, v153
	v_add_f32_e32 v84, v88, v90
	v_sub_f32_e32 v42, v42, v84
	ds_read_b128 v[150:153], v143 offset:6656
	s_waitcnt lgkmcnt(7)
	v_fma_f32 v88, v4, v114, 0
	v_fma_f32 v90, v5, v115, 0
	v_fmac_f32_e32 v88, v80, v116
	v_fmac_f32_e32 v90, v81, v117
	ds_read_b128 v[114:117], v143 offset:6672
	s_waitcnt lgkmcnt(7)
	v_fmac_f32_e32 v88, v82, v118
	v_fmac_f32_e32 v90, v83, v119
	v_fmac_f32_e32 v88, v60, v120
	v_fmac_f32_e32 v90, v61, v121
	ds_read_b128 v[118:121], v143 offset:6688
	s_waitcnt lgkmcnt(7)
	v_fmac_f32_e32 v88, v58, v122
	v_fmac_f32_e32 v90, v59, v123
	v_fmac_f32_e32 v88, v56, v124
	v_fmac_f32_e32 v90, v57, v125
	ds_read_b128 v[122:125], v143 offset:6704
	s_waitcnt lgkmcnt(7)
	v_fmac_f32_e32 v88, v54, v126
	v_fmac_f32_e32 v90, v55, v127
	v_fmac_f32_e32 v88, v52, v128
	v_fmac_f32_e32 v90, v53, v129
	ds_read_b128 v[126:129], v143 offset:6720
	s_waitcnt lgkmcnt(7)
; DI void gdn_g1(const Params& p, int l, int ch, char* smem) {
;     ...
;     for (int cc = 1; cc < 64; ++cc) { float a0 = 0.f, a1 = 0.f;
; #pragma unroll
;       for (int s2 = 0; s2 < cc; ++s2) { if (s2 & 1) a1 += sA[cc * 64 + s2] * sol[s2]; else a0 += sA[cc * 64 + s2] * sol[s2]; }
;       sol[cc] -= a0 + a1; }
	v_fmac_f32_e32 v88, v50, v130
	v_fmac_f32_e32 v90, v51, v131
	v_fmac_f32_e32 v88, v48, v132
	v_fmac_f32_e32 v90, v49, v133
	ds_read_b128 v[130:133], v143 offset:6736
	s_waitcnt lgkmcnt(7)
	v_fmac_f32_e32 v88, v46, v134
	v_fmac_f32_e32 v90, v47, v135
	v_fmac_f32_e32 v88, v44, v136
	v_fmac_f32_e32 v90, v45, v137
	ds_read_b64 v[134:135], v143 offset:6752
	s_waitcnt lgkmcnt(7)
	v_fmac_f32_e32 v88, v42, v146
	v_add_f32_e32 v84, v90, v88
	v_sub_f32_e32 v43, v43, v84
	ds_read_b128 v[146:149], v143 offset:6912
	s_waitcnt lgkmcnt(7)
	v_fma_f32 v88, v4, v150, 0
	v_fma_f32 v90, v5, v151, 0
	v_fmac_f32_e32 v88, v80, v152
	v_fmac_f32_e32 v90, v81, v153
	ds_read_b128 v[150:153], v143 offset:6928
	s_waitcnt lgkmcnt(7)
	v_fmac_f32_e32 v88, v82, v114
	v_fmac_f32_e32 v90, v83, v115
	v_fmac_f32_e32 v88, v60, v116
	v_fmac_f32_e32 v90, v61, v117
	ds_read_b128 v[114:117], v143 offset:6944
	s_waitcnt lgkmcnt(7)
	v_fmac_f32_e32 v88, v58, v118
	v_fmac_f32_e32 v90, v59, v119
	v_fmac_f32_e32 v88, v56, v120
	v_fmac_f32_e32 v90, v57, v121
	ds_read_b128 v[118:121], v143 offset:6960
	s_waitcnt lgkmcnt(7)
	v_fmac_f32_e32 v88, v54, v122
	v_fmac_f32_e32 v90, v55, v123
	v_fmac_f32_e32 v88, v52, v124
	v_fmac_f32_e32 v90, v53, v125
	ds_read_b128 v[122:125], v143 offset:6976
	s_waitcnt lgkmcnt(7)
	v_fmac_f32_e32 v88, v50, v126
	v_fmac_f32_e32 v90, v51, v127
	v_fmac_f32_e32 v88, v48, v128
	v_fmac_f32_e32 v90, v49, v129
	ds_read_b128 v[126:129], v143 offset:6992
	s_waitcnt lgkmcnt(7)
	v_fmac_f32_e32 v88, v46, v130
	v_fmac_f32_e32 v90, v47, v131
	v_fmac_f32_e32 v88, v44, v132
	v_fmac_f32_e32 v90, v45, v133
	ds_read_b96 v[130:132], v143 offset:7008
	s_waitcnt lgkmcnt(7)
	v_fmac_f32_e32 v88, v42, v134
	v_fmac_f32_e32 v90, v43, v135
	v_add_f32_e32 v84, v88, v90
	v_sub_f32_e32 v40, v40, v84
	ds_read_b128 v[134:137], v143 offset:7168
	s_waitcnt lgkmcnt(7)
	v_fma_f32 v88, v4, v146, 0
	v_fma_f32 v90, v5, v147, 0
	v_fmac_f32_e32 v88, v80, v148
	v_fmac_f32_e32 v90, v81, v149
	ds_read_b128 v[146:149], v143 offset:7184
	s_waitcnt lgkmcnt(7)
	v_fmac_f32_e32 v88, v82, v150
	v_fmac_f32_e32 v90, v83, v151
	v_fmac_f32_e32 v88, v60, v152
	v_fmac_f32_e32 v90, v61, v153
	ds_read_b128 v[150:153], v143 offset:7200
	s_waitcnt lgkmcnt(7)
	v_fmac_f32_e32 v88, v58, v114
	v_fmac_f32_e32 v90, v59, v115
	v_fmac_f32_e32 v88, v56, v116
	v_fmac_f32_e32 v90, v57, v117
	ds_read_b128 v[114:117], v143 offset:7216
	s_waitcnt lgkmcnt(7)
	v_fmac_f32_e32 v88, v54, v118
	v_fmac_f32_e32 v90, v55, v119
	v_fmac_f32_e32 v88, v52, v120
	v_fmac_f32_e32 v90, v53, v121
	ds_read_b128 v[118:121], v143 offset:7232
	s_waitcnt lgkmcnt(7)
	v_fmac_f32_e32 v88, v50, v122
	v_fmac_f32_e32 v90, v51, v123
	v_fmac_f32_e32 v88, v48, v124
	v_fmac_f32_e32 v90, v49, v125
	ds_read_b128 v[122:125], v143 offset:7248
	s_waitcnt lgkmcnt(7)
	v_fmac_f32_e32 v88, v46, v126
	v_fmac_f32_e32 v90, v47, v127
	v_fmac_f32_e32 v88, v44, v128
	v_fmac_f32_e32 v90, v45, v129
	ds_read_b128 v[126:129], v143 offset:7264
	s_waitcnt lgkmcnt(7)
	v_fmac_f32_e32 v88, v42, v130
	v_fmac_f32_e32 v90, v43, v131
	v_fmac_f32_e32 v88, v40, v132
	v_add_f32_e32 v84, v90, v88
	v_sub_f32_e32 v41, v41, v84
	ds_read_b128 v[130:133], v143 offset:7424
	s_waitcnt lgkmcnt(7)
	v_fma_f32 v88, v4, v134, 0
	v_fma_f32 v90, v5, v135, 0
	v_fmac_f32_e32 v88, v80, v136
	v_fmac_f32_e32 v90, v81, v137
	ds_read_b128 v[134:137], v143 offset:7440
	s_waitcnt lgkmcnt(7)
	v_fmac_f32_e32 v88, v82, v146
	v_fmac_f32_e32 v90, v83, v147
	v_fmac_f32_e32 v88, v60, v148
	v_fmac_f32_e32 v90, v61, v149
	ds_read_b128 v[146:149], v143 offset:7456
	s_waitcnt lgkmcnt(7)
	v_fmac_f32_e32 v88, v58, v150
	v_fmac_f32_e32 v90, v59, v151
	v_fmac_f32_e32 v88, v56, v152
	v_fmac_f32_e32 v90, v57, v153
	ds_read_b128 v[150:153], v143 offset:7472
	s_waitcnt lgkmcnt(7)
	v_fmac_f32_e32 v88, v54, v114
	v_fmac_f32_e32 v90, v55, v115
	v_fmac_f32_e32 v88, v52, v116
	v_fmac_f32_e32 v90, v53, v117
	ds_read_b128 v[114:117], v143 offset:7488
	s_waitcnt lgkmcnt(7)
	v_fmac_f32_e32 v88, v50, v118
	v_fmac_f32_e32 v90, v51, v119
	v_fmac_f32_e32 v88, v48, v120
	v_fmac_f32_e32 v90, v49, v121
	ds_read_b128 v[118:121], v143 offset:7504
	s_waitcnt lgkmcnt(7)
	v_fmac_f32_e32 v88, v46, v122
	v_fmac_f32_e32 v90, v47, v123
	v_fmac_f32_e32 v88, v44, v124
	v_fmac_f32_e32 v90, v45, v125
	ds_read_b128 v[122:125], v143 offset:7520
	s_waitcnt lgkmcnt(7)
	v_fmac_f32_e32 v88, v42, v126
	v_fmac_f32_e32 v90, v43, v127
	v_fmac_f32_e32 v88, v40, v128
	v_fmac_f32_e32 v90, v41, v129
	v_add_f32_e32 v84, v88, v90
	v_sub_f32_e32 v38, v38, v84
	ds_read_b32 v126, v143 offset:7536
	s_waitcnt lgkmcnt(7)
	v_fma_f32 v88, v4, v130, 0
	v_fma_f32 v90, v5, v131, 0
	v_fmac_f32_e32 v88, v80, v132
	v_fmac_f32_e32 v90, v81, v133
	ds_read_b128 v[130:133], v143 offset:7680
	s_waitcnt lgkmcnt(7)
	v_fmac_f32_e32 v88, v82, v134
	v_fmac_f32_e32 v90, v83, v135
	v_fmac_f32_e32 v88, v60, v136
	v_fmac_f32_e32 v90, v61, v137
	ds_read_b128 v[134:137], v143 offset:7696
	s_waitcnt lgkmcnt(7)
	v_fmac_f32_e32 v88, v58, v146
	v_fmac_f32_e32 v90, v59, v147
	v_fmac_f32_e32 v88, v56, v148
	v_fmac_f32_e32 v90, v57, v149
	ds_read_b128 v[146:149], v143 offset:7712
	s_waitcnt lgkmcnt(7)
	v_fmac_f32_e32 v88, v54, v150
	v_fmac_f32_e32 v90, v55, v151
	v_fmac_f32_e32 v88, v52, v152
	v_fmac_f32_e32 v90, v53, v153
	ds_read_b128 v[150:153], v143 offset:7728
	s_waitcnt lgkmcnt(7)
	v_fmac_f32_e32 v88, v50, v114
	v_fmac_f32_e32 v90, v51, v115
	v_fmac_f32_e32 v88, v48, v116
	v_fmac_f32_e32 v90, v49, v117
	ds_read_b128 v[114:117], v143 offset:7744
	s_waitcnt lgkmcnt(7)
	v_fmac_f32_e32 v88, v46, v118
	v_fmac_f32_e32 v90, v47, v119
	v_fmac_f32_e32 v88, v44, v120
	v_fmac_f32_e32 v90, v45, v121
	ds_read_b128 v[118:121], v143 offset:7760
	s_waitcnt lgkmcnt(7)
; DI void gdn_g1(const Params& p, int l, int ch, char* smem) {
;     ...
;     for (int cc = 1; cc < 64; ++cc) { float a0 = 0.f, a1 = 0.f;
; #pragma unroll
;       for (int s2 = 0; s2 < cc; ++s2) { if (s2 & 1) a1 += sA[cc * 64 + s2] * sol[s2]; else a0 += sA[cc * 64 + s2] * sol[s2]; }
;       sol[cc] -= a0 + a1; }
	v_fmac_f32_e32 v88, v42, v122
	v_fmac_f32_e32 v90, v43, v123
	v_fmac_f32_e32 v88, v40, v124
	v_fmac_f32_e32 v90, v41, v125
	ds_read_b128 v[122:125], v143 offset:7776
	s_waitcnt lgkmcnt(7)
	v_fmac_f32_e32 v88, v38, v126
	v_add_f32_e32 v84, v90, v88
	v_sub_f32_e32 v39, v39, v84
	ds_read_b64 v[126:127], v143 offset:7792
	s_waitcnt lgkmcnt(7)
	v_fma_f32 v88, v4, v130, 0
	v_fma_f32 v90, v5, v131, 0
	v_fmac_f32_e32 v88, v80, v132
	v_fmac_f32_e32 v90, v81, v133
	ds_read_b128 v[130:133], v143 offset:7936
	s_waitcnt lgkmcnt(7)
	v_fmac_f32_e32 v88, v82, v134
	v_fmac_f32_e32 v90, v83, v135
	v_fmac_f32_e32 v88, v60, v136
	v_fmac_f32_e32 v90, v61, v137
	ds_read_b128 v[134:137], v143 offset:7952
	s_waitcnt lgkmcnt(7)
	v_fmac_f32_e32 v88, v58, v146
	v_fmac_f32_e32 v90, v59, v147
	v_fmac_f32_e32 v88, v56, v148
	v_fmac_f32_e32 v90, v57, v149
	ds_read_b128 v[146:149], v143 offset:7968
	s_waitcnt lgkmcnt(7)
	v_fmac_f32_e32 v88, v54, v150
	v_fmac_f32_e32 v90, v55, v151
	v_fmac_f32_e32 v88, v52, v152
	v_fmac_f32_e32 v90, v53, v153
	ds_read_b128 v[150:153], v143 offset:7984
	s_waitcnt lgkmcnt(7)
	v_fmac_f32_e32 v88, v50, v114
	v_fmac_f32_e32 v90, v51, v115
	v_fmac_f32_e32 v88, v48, v116
	v_fmac_f32_e32 v90, v49, v117
	ds_read_b128 v[114:117], v143 offset:8000
	s_waitcnt lgkmcnt(7)
	v_fmac_f32_e32 v88, v46, v118
	v_fmac_f32_e32 v90, v47, v119
	v_fmac_f32_e32 v88, v44, v120
	v_fmac_f32_e32 v90, v45, v121
	ds_read_b128 v[118:121], v143 offset:8016
	s_waitcnt lgkmcnt(7)
	v_fmac_f32_e32 v88, v42, v122
	v_fmac_f32_e32 v90, v43, v123
	v_fmac_f32_e32 v88, v40, v124
	v_fmac_f32_e32 v90, v41, v125
	ds_read_b128 v[122:125], v143 offset:8032
	s_waitcnt lgkmcnt(7)
	v_fmac_f32_e32 v88, v38, v126
	v_fmac_f32_e32 v90, v39, v127
	v_add_f32_e32 v84, v88, v90
	v_sub_f32_e32 v36, v36, v84
	ds_read_b96 v[126:128], v143 offset:8048
	s_waitcnt lgkmcnt(7)
	v_fma_f32 v88, v4, v130, 0
	v_fma_f32 v90, v5, v131, 0
	v_fmac_f32_e32 v88, v80, v132
	v_fmac_f32_e32 v90, v81, v133
	ds_read_b128 v[130:133], v143 offset:8192
	s_waitcnt lgkmcnt(7)
	v_fmac_f32_e32 v88, v82, v134
	v_fmac_f32_e32 v90, v83, v135
	v_fmac_f32_e32 v88, v60, v136
	v_fmac_f32_e32 v90, v61, v137
	ds_read_b128 v[134:137], v143 offset:8208
	s_waitcnt lgkmcnt(7)
	v_fmac_f32_e32 v88, v58, v146
	v_fmac_f32_e32 v90, v59, v147
	v_fmac_f32_e32 v88, v56, v148
	v_fmac_f32_e32 v90, v57, v149
	ds_read_b128 v[146:149], v143 offset:8224
	s_waitcnt lgkmcnt(7)
	v_fmac_f32_e32 v88, v54, v150
	v_fmac_f32_e32 v90, v55, v151
	v_fmac_f32_e32 v88, v52, v152
	v_fmac_f32_e32 v90, v53, v153
	ds_read_b128 v[150:153], v143 offset:8240
	s_waitcnt lgkmcnt(7)
	v_fmac_f32_e32 v88, v50, v114
	v_fmac_f32_e32 v90, v51, v115
	v_fmac_f32_e32 v88, v48, v116
	v_fmac_f32_e32 v90, v49, v117
	ds_read_b128 v[114:117], v143 offset:8256
	s_waitcnt lgkmcnt(7)
	v_fmac_f32_e32 v88, v46, v118
	v_fmac_f32_e32 v90, v47, v119
	v_fmac_f32_e32 v88, v44, v120
	v_fmac_f32_e32 v90, v45, v121
	ds_read_b128 v[118:121], v143 offset:8272
	s_waitcnt lgkmcnt(7)
	v_fmac_f32_e32 v88, v42, v122
	v_fmac_f32_e32 v90, v43, v123
	v_fmac_f32_e32 v88, v40, v124
	v_fmac_f32_e32 v90, v41, v125
	ds_read_b128 v[122:125], v143 offset:8288
	s_waitcnt lgkmcnt(7)
	v_fmac_f32_e32 v88, v38, v126
	v_fmac_f32_e32 v90, v39, v127
	v_fmac_f32_e32 v88, v36, v128
	v_add_f32_e32 v84, v90, v88
	v_sub_f32_e32 v37, v37, v84
	ds_read_b128 v[126:129], v143 offset:8304
	s_waitcnt lgkmcnt(7)
	v_fma_f32 v88, v4, v130, 0
	v_fma_f32 v90, v5, v131, 0
	v_fmac_f32_e32 v88, v80, v132
	v_fmac_f32_e32 v90, v81, v133
	ds_read_b128 v[130:133], v143 offset:8448
	s_waitcnt lgkmcnt(7)
	v_fmac_f32_e32 v88, v82, v134
	v_fmac_f32_e32 v90, v83, v135
	v_fmac_f32_e32 v88, v60, v136
	v_fmac_f32_e32 v90, v61, v137
	ds_read_b128 v[134:137], v143 offset:8464
	s_waitcnt lgkmcnt(7)
	v_fmac_f32_e32 v88, v58, v146
	v_fmac_f32_e32 v90, v59, v147
	v_fmac_f32_e32 v88, v56, v148
	v_fmac_f32_e32 v90, v57, v149
	ds_read_b128 v[146:149], v143 offset:8480
	s_waitcnt lgkmcnt(7)
	v_fmac_f32_e32 v88, v54, v150
	v_fmac_f32_e32 v90, v55, v151
	v_fmac_f32_e32 v88, v52, v152
	v_fmac_f32_e32 v90, v53, v153
	ds_read_b128 v[150:153], v143 offset:8496
	s_waitcnt lgkmcnt(7)
	v_fmac_f32_e32 v88, v50, v114
	v_fmac_f32_e32 v90, v51, v115
	v_fmac_f32_e32 v88, v48, v116
	v_fmac_f32_e32 v90, v49, v117
	ds_read_b128 v[114:117], v143 offset:8512
	s_waitcnt lgkmcnt(7)
	v_fmac_f32_e32 v88, v46, v118
	v_fmac_f32_e32 v90, v47, v119
	v_fmac_f32_e32 v88, v44, v120
	v_fmac_f32_e32 v90, v45, v121
	ds_read_b128 v[118:121], v143 offset:8528
	s_waitcnt lgkmcnt(7)
	v_fmac_f32_e32 v88, v42, v122
	v_fmac_f32_e32 v90, v43, v123
	v_fmac_f32_e32 v88, v40, v124
	v_fmac_f32_e32 v90, v41, v125
	ds_read_b128 v[122:125], v143 offset:8544
	s_waitcnt lgkmcnt(7)
	v_fmac_f32_e32 v88, v38, v126
	v_fmac_f32_e32 v90, v39, v127
	v_fmac_f32_e32 v88, v36, v128
	v_fmac_f32_e32 v90, v37, v129
	v_add_f32_e32 v84, v88, v90
	v_sub_f32_e32 v34, v34, v84
	ds_read_b128 v[126:129], v143 offset:8560
	s_waitcnt lgkmcnt(7)
	v_fma_f32 v88, v4, v130, 0
	v_fma_f32 v90, v5, v131, 0
	v_fmac_f32_e32 v88, v80, v132
	v_fmac_f32_e32 v90, v81, v133
	ds_read_b32 v130, v143 offset:8576
	s_waitcnt lgkmcnt(7)
	v_fmac_f32_e32 v88, v82, v134
	v_fmac_f32_e32 v90, v83, v135
	v_fmac_f32_e32 v88, v60, v136
	v_fmac_f32_e32 v90, v61, v137
	ds_read_b128 v[134:137], v143 offset:8704
	s_waitcnt lgkmcnt(7)
	v_fmac_f32_e32 v88, v58, v146
	v_fmac_f32_e32 v90, v59, v147
	v_fmac_f32_e32 v88, v56, v148
	v_fmac_f32_e32 v90, v57, v149
	ds_read_b128 v[146:149], v143 offset:8720
	s_waitcnt lgkmcnt(7)
	v_fmac_f32_e32 v88, v54, v150
	v_fmac_f32_e32 v90, v55, v151
	v_fmac_f32_e32 v88, v52, v152
	v_fmac_f32_e32 v90, v53, v153
	ds_read_b128 v[150:153], v143 offset:8736
	s_waitcnt lgkmcnt(7)
; DI void gdn_g1(const Params& p, int l, int ch, char* smem) {
;     ...
;     for (int cc = 1; cc < 64; ++cc) { float a0 = 0.f, a1 = 0.f;
; #pragma unroll
;       for (int s2 = 0; s2 < cc; ++s2) { if (s2 & 1) a1 += sA[cc * 64 + s2] * sol[s2]; else a0 += sA[cc * 64 + s2] * sol[s2]; }
;       sol[cc] -= a0 + a1; }
	v_fmac_f32_e32 v88, v50, v114
	v_fmac_f32_e32 v90, v51, v115
	v_fmac_f32_e32 v88, v48, v116
	v_fmac_f32_e32 v90, v49, v117
	ds_read_b128 v[114:117], v143 offset:8752
	s_waitcnt lgkmcnt(7)
	v_fmac_f32_e32 v88, v46, v118
	v_fmac_f32_e32 v90, v47, v119
	v_fmac_f32_e32 v88, v44, v120
	v_fmac_f32_e32 v90, v45, v121
	ds_read_b128 v[118:121], v143 offset:8768
	s_waitcnt lgkmcnt(7)
	v_fmac_f32_e32 v88, v42, v122
	v_fmac_f32_e32 v90, v43, v123
	v_fmac_f32_e32 v88, v40, v124
	v_fmac_f32_e32 v90, v41, v125
	ds_read_b128 v[122:125], v143 offset:8784
	s_waitcnt lgkmcnt(7)
	v_fmac_f32_e32 v88, v38, v126
	v_fmac_f32_e32 v90, v39, v127
	v_fmac_f32_e32 v88, v36, v128
	v_fmac_f32_e32 v90, v37, v129
	ds_read_b128 v[126:129], v143 offset:8800
	s_waitcnt lgkmcnt(7)
	v_fmac_f32_e32 v88, v34, v130
	v_add_f32_e32 v84, v90, v88
	v_sub_f32_e32 v35, v35, v84
	ds_read_b128 v[130:133], v143 offset:8816
	s_waitcnt lgkmcnt(7)
	v_fma_f32 v88, v4, v134, 0
	v_fma_f32 v90, v5, v135, 0
	v_fmac_f32_e32 v88, v80, v136
	v_fmac_f32_e32 v90, v81, v137
	ds_read_b64 v[134:135], v143 offset:8832
	s_waitcnt lgkmcnt(7)
	v_fmac_f32_e32 v88, v82, v146
	v_fmac_f32_e32 v90, v83, v147
	v_fmac_f32_e32 v88, v60, v148
	v_fmac_f32_e32 v90, v61, v149
	ds_read_b128 v[146:149], v143 offset:8960
	s_waitcnt lgkmcnt(7)
	v_fmac_f32_e32 v88, v58, v150
	v_fmac_f32_e32 v90, v59, v151
	v_fmac_f32_e32 v88, v56, v152
	v_fmac_f32_e32 v90, v57, v153
	ds_read_b128 v[150:153], v143 offset:8976
	s_waitcnt lgkmcnt(7)
	v_fmac_f32_e32 v88, v54, v114
	v_fmac_f32_e32 v90, v55, v115
	v_fmac_f32_e32 v88, v52, v116
	v_fmac_f32_e32 v90, v53, v117
	ds_read_b128 v[114:117], v143 offset:8992
	s_waitcnt lgkmcnt(7)
	v_fmac_f32_e32 v88, v50, v118
	v_fmac_f32_e32 v90, v51, v119
	v_fmac_f32_e32 v88, v48, v120
	v_fmac_f32_e32 v90, v49, v121
	ds_read_b128 v[118:121], v143 offset:9008
	s_waitcnt lgkmcnt(7)
	v_fmac_f32_e32 v88, v46, v122
	v_fmac_f32_e32 v90, v47, v123
	v_fmac_f32_e32 v88, v44, v124
	v_fmac_f32_e32 v90, v45, v125
	ds_read_b128 v[122:125], v143 offset:9024
	s_waitcnt lgkmcnt(7)
	v_fmac_f32_e32 v88, v42, v126
	v_fmac_f32_e32 v90, v43, v127
	v_fmac_f32_e32 v88, v40, v128
	v_fmac_f32_e32 v90, v41, v129
	ds_read_b128 v[126:129], v143 offset:9040
	s_waitcnt lgkmcnt(7)
	v_fmac_f32_e32 v88, v38, v130
	v_fmac_f32_e32 v90, v39, v131
	v_fmac_f32_e32 v88, v36, v132
	v_fmac_f32_e32 v90, v37, v133
	ds_read_b128 v[130:133], v143 offset:9056
	s_waitcnt lgkmcnt(7)
	v_fmac_f32_e32 v88, v34, v134
	v_fmac_f32_e32 v90, v35, v135
	v_add_f32_e32 v84, v88, v90
	v_sub_f32_e32 v32, v32, v84
	ds_read_b128 v[134:137], v143 offset:9072
	s_waitcnt lgkmcnt(7)
	v_fma_f32 v88, v4, v146, 0
	v_fma_f32 v90, v5, v147, 0
	v_fmac_f32_e32 v88, v80, v148
	v_fmac_f32_e32 v90, v81, v149
	ds_read_b96 v[146:148], v143 offset:9088
	s_waitcnt lgkmcnt(7)
	v_fmac_f32_e32 v88, v82, v150
	v_fmac_f32_e32 v90, v83, v151
	v_fmac_f32_e32 v88, v60, v152
	v_fmac_f32_e32 v90, v61, v153
	ds_read_b128 v[150:153], v143 offset:9216
	s_waitcnt lgkmcnt(7)
	v_fmac_f32_e32 v88, v58, v114
	v_fmac_f32_e32 v90, v59, v115
	v_fmac_f32_e32 v88, v56, v116
	v_fmac_f32_e32 v90, v57, v117
	ds_read_b128 v[114:117], v143 offset:9232
	s_waitcnt lgkmcnt(7)
	v_fmac_f32_e32 v88, v54, v118
	v_fmac_f32_e32 v90, v55, v119
	v_fmac_f32_e32 v88, v52, v120
	v_fmac_f32_e32 v90, v53, v121
	ds_read_b128 v[118:121], v143 offset:9248
	s_waitcnt lgkmcnt(7)
	v_fmac_f32_e32 v88, v50, v122
	v_fmac_f32_e32 v90, v51, v123
	v_fmac_f32_e32 v88, v48, v124
	v_fmac_f32_e32 v90, v49, v125
	ds_read_b128 v[122:125], v143 offset:9264
	s_waitcnt lgkmcnt(7)
	v_fmac_f32_e32 v88, v46, v126
	v_fmac_f32_e32 v90, v47, v127
	v_fmac_f32_e32 v88, v44, v128
	v_fmac_f32_e32 v90, v45, v129
	ds_read_b128 v[126:129], v143 offset:9280
	s_waitcnt lgkmcnt(7)
	v_fmac_f32_e32 v88, v42, v130
	v_fmac_f32_e32 v90, v43, v131
	v_fmac_f32_e32 v88, v40, v132
	v_fmac_f32_e32 v90, v41, v133
	ds_read_b128 v[130:133], v143 offset:9296
	s_waitcnt lgkmcnt(7)
	v_fmac_f32_e32 v88, v38, v134
	v_fmac_f32_e32 v90, v39, v135
	v_fmac_f32_e32 v88, v36, v136
	v_fmac_f32_e32 v90, v37, v137
	ds_read_b128 v[134:137], v143 offset:9312
	s_waitcnt lgkmcnt(7)
	v_fmac_f32_e32 v88, v34, v146
	v_fmac_f32_e32 v90, v35, v147
	v_fmac_f32_e32 v88, v32, v148
	v_add_f32_e32 v84, v90, v88
	v_sub_f32_e32 v33, v33, v84
	ds_read_b128 v[146:149], v143 offset:9328
	s_waitcnt lgkmcnt(7)
	v_fma_f32 v88, v4, v150, 0
	v_fma_f32 v90, v5, v151, 0
	v_fmac_f32_e32 v88, v80, v152
	v_fmac_f32_e32 v90, v81, v153
	ds_read_b128 v[150:153], v143 offset:9344
	s_waitcnt lgkmcnt(7)
	v_fmac_f32_e32 v88, v82, v114
	v_fmac_f32_e32 v90, v83, v115
	v_fmac_f32_e32 v88, v60, v116
	v_fmac_f32_e32 v90, v61, v117
	ds_read_b128 v[114:117], v143 offset:9472
	s_waitcnt lgkmcnt(7)
	v_fmac_f32_e32 v88, v58, v118
	v_fmac_f32_e32 v90, v59, v119
	v_fmac_f32_e32 v88, v56, v120
	v_fmac_f32_e32 v90, v57, v121
	ds_read_b128 v[118:121], v143 offset:9488
	s_waitcnt lgkmcnt(7)
	v_fmac_f32_e32 v88, v54, v122
	v_fmac_f32_e32 v90, v55, v123
	v_fmac_f32_e32 v88, v52, v124
	v_fmac_f32_e32 v90, v53, v125
	ds_read_b128 v[122:125], v143 offset:9504
	s_waitcnt lgkmcnt(7)
	v_fmac_f32_e32 v88, v50, v126
	v_fmac_f32_e32 v90, v51, v127
	v_fmac_f32_e32 v88, v48, v128
	v_fmac_f32_e32 v90, v49, v129
	ds_read_b128 v[126:129], v143 offset:9520
	s_waitcnt lgkmcnt(7)
	v_fmac_f32_e32 v88, v46, v130
	v_fmac_f32_e32 v90, v47, v131
	v_fmac_f32_e32 v88, v44, v132
	v_fmac_f32_e32 v90, v45, v133
	ds_read_b128 v[130:133], v143 offset:9536
	s_waitcnt lgkmcnt(7)
	v_fmac_f32_e32 v88, v42, v134
	v_fmac_f32_e32 v90, v43, v135
	v_fmac_f32_e32 v88, v40, v136
	v_fmac_f32_e32 v90, v41, v137
	ds_read_b128 v[134:137], v143 offset:9552
	s_waitcnt lgkmcnt(7)
; DI void gdn_g1(const Params& p, int l, int ch, char* smem) {
;     ...
;     for (int cc = 1; cc < 64; ++cc) { float a0 = 0.f, a1 = 0.f;
; #pragma unroll
;       for (int s2 = 0; s2 < cc; ++s2) { if (s2 & 1) a1 += sA[cc * 64 + s2] * sol[s2]; else a0 += sA[cc * 64 + s2] * sol[s2]; }
;       sol[cc] -= a0 + a1; }
	v_fmac_f32_e32 v88, v38, v146
	v_fmac_f32_e32 v90, v39, v147
	v_fmac_f32_e32 v88, v36, v148
	v_fmac_f32_e32 v90, v37, v149
	ds_read_b128 v[146:149], v143 offset:9568
	s_waitcnt lgkmcnt(7)
	v_fmac_f32_e32 v88, v34, v150
	v_fmac_f32_e32 v90, v35, v151
	v_fmac_f32_e32 v88, v32, v152
	v_fmac_f32_e32 v90, v33, v153
	v_add_f32_e32 v84, v88, v90
	v_sub_f32_e32 v30, v30, v84
	ds_read_b128 v[150:153], v143 offset:9584
	s_waitcnt lgkmcnt(7)
	v_fma_f32 v88, v4, v114, 0
	v_fma_f32 v90, v5, v115, 0
	v_fmac_f32_e32 v88, v80, v116
	v_fmac_f32_e32 v90, v81, v117
	ds_read_b128 v[114:117], v143 offset:9600
	s_waitcnt lgkmcnt(7)
	v_fmac_f32_e32 v88, v82, v118
	v_fmac_f32_e32 v90, v83, v119
	v_fmac_f32_e32 v88, v60, v120
	v_fmac_f32_e32 v90, v61, v121
	ds_read_b32 v118, v143 offset:9616
	s_waitcnt lgkmcnt(7)
	v_fmac_f32_e32 v88, v58, v122
	v_fmac_f32_e32 v90, v59, v123
	v_fmac_f32_e32 v88, v56, v124
	v_fmac_f32_e32 v90, v57, v125
	ds_read_b128 v[122:125], v143 offset:9728
	s_waitcnt lgkmcnt(7)
	v_fmac_f32_e32 v88, v54, v126
	v_fmac_f32_e32 v90, v55, v127
	v_fmac_f32_e32 v88, v52, v128
	v_fmac_f32_e32 v90, v53, v129
	ds_read_b128 v[126:129], v143 offset:9744
	s_waitcnt lgkmcnt(7)
	v_fmac_f32_e32 v88, v50, v130
	v_fmac_f32_e32 v90, v51, v131
	v_fmac_f32_e32 v88, v48, v132
	v_fmac_f32_e32 v90, v49, v133
	ds_read_b128 v[130:133], v143 offset:9760
	s_waitcnt lgkmcnt(7)
	v_fmac_f32_e32 v88, v46, v134
	v_fmac_f32_e32 v90, v47, v135
	v_fmac_f32_e32 v88, v44, v136
	v_fmac_f32_e32 v90, v45, v137
	ds_read_b128 v[134:137], v143 offset:9776
	s_waitcnt lgkmcnt(7)
	v_fmac_f32_e32 v88, v42, v146
	v_fmac_f32_e32 v90, v43, v147
	v_fmac_f32_e32 v88, v40, v148
	v_fmac_f32_e32 v90, v41, v149
	ds_read_b128 v[146:149], v143 offset:9792
	s_waitcnt lgkmcnt(7)
	v_fmac_f32_e32 v88, v38, v150
	v_fmac_f32_e32 v90, v39, v151
	v_fmac_f32_e32 v88, v36, v152
	v_fmac_f32_e32 v90, v37, v153
	ds_read_b128 v[150:153], v143 offset:9808
	s_waitcnt lgkmcnt(7)
	v_fmac_f32_e32 v88, v34, v114
	v_fmac_f32_e32 v90, v35, v115
	v_fmac_f32_e32 v88, v32, v116
	v_fmac_f32_e32 v90, v33, v117
	ds_read_b128 v[114:117], v143 offset:9824
	s_waitcnt lgkmcnt(7)
	v_fmac_f32_e32 v88, v30, v118
	v_add_f32_e32 v84, v90, v88
	v_sub_f32_e32 v31, v31, v84
	ds_read_b128 v[118:121], v143 offset:9840
	s_waitcnt lgkmcnt(7)
	v_fma_f32 v88, v4, v122, 0
	v_fma_f32 v90, v5, v123, 0
	v_fmac_f32_e32 v88, v80, v124
	v_fmac_f32_e32 v90, v81, v125
	ds_read_b128 v[122:125], v143 offset:9856
	s_waitcnt lgkmcnt(7)
	v_fmac_f32_e32 v88, v82, v126
	v_fmac_f32_e32 v90, v83, v127
	v_fmac_f32_e32 v88, v60, v128
	v_fmac_f32_e32 v90, v61, v129
	ds_read_b64 v[126:127], v143 offset:9872
	s_waitcnt lgkmcnt(7)
	v_fmac_f32_e32 v88, v58, v130
	v_fmac_f32_e32 v90, v59, v131
	v_fmac_f32_e32 v88, v56, v132
	v_fmac_f32_e32 v90, v57, v133
	ds_read_b128 v[130:133], v143 offset:9984
	s_waitcnt lgkmcnt(7)
	v_fmac_f32_e32 v88, v54, v134
	v_fmac_f32_e32 v90, v55, v135
	v_fmac_f32_e32 v88, v52, v136
	v_fmac_f32_e32 v90, v53, v137
	ds_read_b128 v[134:137], v143 offset:10000
	s_waitcnt lgkmcnt(7)
	v_fmac_f32_e32 v88, v50, v146
	v_fmac_f32_e32 v90, v51, v147
	v_fmac_f32_e32 v88, v48, v148
	v_fmac_f32_e32 v90, v49, v149
	ds_read_b128 v[146:149], v143 offset:10016
	s_waitcnt lgkmcnt(7)
	v_fmac_f32_e32 v88, v46, v150
	v_fmac_f32_e32 v90, v47, v151
	v_fmac_f32_e32 v88, v44, v152
	v_fmac_f32_e32 v90, v45, v153
	ds_read_b128 v[150:153], v143 offset:10032
	s_waitcnt lgkmcnt(7)
	v_fmac_f32_e32 v88, v42, v114
	v_fmac_f32_e32 v90, v43, v115
	v_fmac_f32_e32 v88, v40, v116
	v_fmac_f32_e32 v90, v41, v117
	ds_read_b128 v[114:117], v143 offset:10048
	s_waitcnt lgkmcnt(7)
	v_fmac_f32_e32 v88, v38, v118
	v_fmac_f32_e32 v90, v39, v119
	v_fmac_f32_e32 v88, v36, v120
	v_fmac_f32_e32 v90, v37, v121
	ds_read_b128 v[118:121], v143 offset:10064
	s_waitcnt lgkmcnt(7)
	v_fmac_f32_e32 v88, v34, v122
	v_fmac_f32_e32 v90, v35, v123
	v_fmac_f32_e32 v88, v32, v124
	v_fmac_f32_e32 v90, v33, v125
	ds_read_b128 v[122:125], v143 offset:10080
	s_waitcnt lgkmcnt(7)
	v_fmac_f32_e32 v88, v30, v126
	v_fmac_f32_e32 v90, v31, v127
	v_add_f32_e32 v84, v88, v90
	v_sub_f32_e32 v28, v28, v84
	ds_read_b128 v[126:129], v143 offset:10096
	s_waitcnt lgkmcnt(7)
	v_fma_f32 v88, v4, v130, 0
	v_fma_f32 v90, v5, v131, 0
	v_fmac_f32_e32 v88, v80, v132
	v_fmac_f32_e32 v90, v81, v133
	ds_read_b128 v[130:133], v143 offset:10112
	s_waitcnt lgkmcnt(7)
	v_fmac_f32_e32 v88, v82, v134
	v_fmac_f32_e32 v90, v83, v135
	v_fmac_f32_e32 v88, v60, v136
	v_fmac_f32_e32 v90, v61, v137
	ds_read_b96 v[134:136], v143 offset:10128
	s_waitcnt lgkmcnt(7)
	v_fmac_f32_e32 v88, v58, v146
	v_fmac_f32_e32 v90, v59, v147
	v_fmac_f32_e32 v88, v56, v148
	v_fmac_f32_e32 v90, v57, v149
	ds_read_b128 v[146:149], v143 offset:10240
	s_waitcnt lgkmcnt(7)
	v_fmac_f32_e32 v88, v54, v150
	v_fmac_f32_e32 v90, v55, v151
	v_fmac_f32_e32 v88, v52, v152
	v_fmac_f32_e32 v90, v53, v153
	ds_read_b128 v[150:153], v143 offset:10256
	s_waitcnt lgkmcnt(7)
	v_fmac_f32_e32 v88, v50, v114
	v_fmac_f32_e32 v90, v51, v115
	v_fmac_f32_e32 v88, v48, v116
	v_fmac_f32_e32 v90, v49, v117
	ds_read_b128 v[114:117], v143 offset:10272
	s_waitcnt lgkmcnt(7)
	v_fmac_f32_e32 v88, v46, v118
	v_fmac_f32_e32 v90, v47, v119
	v_fmac_f32_e32 v88, v44, v120
	v_fmac_f32_e32 v90, v45, v121
	ds_read_b128 v[118:121], v143 offset:10288
	s_waitcnt lgkmcnt(7)
	v_fmac_f32_e32 v88, v42, v122
	v_fmac_f32_e32 v90, v43, v123
	v_fmac_f32_e32 v88, v40, v124
	v_fmac_f32_e32 v90, v41, v125
	ds_read_b128 v[122:125], v143 offset:10304
	s_waitcnt lgkmcnt(7)
	v_fmac_f32_e32 v88, v38, v126
	v_fmac_f32_e32 v90, v39, v127
	v_fmac_f32_e32 v88, v36, v128
	v_fmac_f32_e32 v90, v37, v129
	ds_read_b128 v[126:129], v143 offset:10320
	s_waitcnt lgkmcnt(7)
; DI void gdn_g1(const Params& p, int l, int ch, char* smem) {
;     ...
;     for (int cc = 1; cc < 64; ++cc) { float a0 = 0.f, a1 = 0.f;
; #pragma unroll
;       for (int s2 = 0; s2 < cc; ++s2) { if (s2 & 1) a1 += sA[cc * 64 + s2] * sol[s2]; else a0 += sA[cc * 64 + s2] * sol[s2]; }
;       sol[cc] -= a0 + a1; }
	v_fmac_f32_e32 v88, v34, v130
	v_fmac_f32_e32 v90, v35, v131
	v_fmac_f32_e32 v88, v32, v132
	v_fmac_f32_e32 v90, v33, v133
	ds_read_b128 v[130:133], v143 offset:10336
	s_waitcnt lgkmcnt(7)
	v_fmac_f32_e32 v88, v30, v134
	v_fmac_f32_e32 v90, v31, v135
	v_fmac_f32_e32 v88, v28, v136
	v_add_f32_e32 v84, v90, v88
	v_sub_f32_e32 v29, v29, v84
	ds_read_b128 v[134:137], v143 offset:10352
	s_waitcnt lgkmcnt(7)
	v_fma_f32 v88, v4, v146, 0
	v_fma_f32 v90, v5, v147, 0
	v_fmac_f32_e32 v88, v80, v148
	v_fmac_f32_e32 v90, v81, v149
	ds_read_b128 v[146:149], v143 offset:10368
	s_waitcnt lgkmcnt(7)
	v_fmac_f32_e32 v88, v82, v150
	v_fmac_f32_e32 v90, v83, v151
	v_fmac_f32_e32 v88, v60, v152
	v_fmac_f32_e32 v90, v61, v153
	ds_read_b128 v[150:153], v143 offset:10384
	s_waitcnt lgkmcnt(7)
	v_fmac_f32_e32 v88, v58, v114
	v_fmac_f32_e32 v90, v59, v115
	v_fmac_f32_e32 v88, v56, v116
	v_fmac_f32_e32 v90, v57, v117
	ds_read_b128 v[114:117], v143 offset:10496
	s_waitcnt lgkmcnt(7)
	v_fmac_f32_e32 v88, v54, v118
	v_fmac_f32_e32 v90, v55, v119
	v_fmac_f32_e32 v88, v52, v120
	v_fmac_f32_e32 v90, v53, v121
	ds_read_b128 v[118:121], v143 offset:10512
	s_waitcnt lgkmcnt(7)
	v_fmac_f32_e32 v88, v50, v122
	v_fmac_f32_e32 v90, v51, v123
	v_fmac_f32_e32 v88, v48, v124
	v_fmac_f32_e32 v90, v49, v125
	ds_read_b128 v[122:125], v143 offset:10528
	s_waitcnt lgkmcnt(7)
	v_fmac_f32_e32 v88, v46, v126
	v_fmac_f32_e32 v90, v47, v127
	v_fmac_f32_e32 v88, v44, v128
	v_fmac_f32_e32 v90, v45, v129
	ds_read_b128 v[126:129], v143 offset:10544
	s_waitcnt lgkmcnt(7)
	v_fmac_f32_e32 v88, v42, v130
	v_fmac_f32_e32 v90, v43, v131
	v_fmac_f32_e32 v88, v40, v132
	v_fmac_f32_e32 v90, v41, v133
	ds_read_b128 v[130:133], v143 offset:10560
	s_waitcnt lgkmcnt(7)
	v_fmac_f32_e32 v88, v38, v134
	v_fmac_f32_e32 v90, v39, v135
	v_fmac_f32_e32 v88, v36, v136
	v_fmac_f32_e32 v90, v37, v137
	ds_read_b128 v[134:137], v143 offset:10576
	s_waitcnt lgkmcnt(7)
	v_fmac_f32_e32 v88, v34, v146
	v_fmac_f32_e32 v90, v35, v147
	v_fmac_f32_e32 v88, v32, v148
	v_fmac_f32_e32 v90, v33, v149
	ds_read_b128 v[146:149], v143 offset:10592
	s_waitcnt lgkmcnt(7)
	v_fmac_f32_e32 v88, v30, v150
	v_fmac_f32_e32 v90, v31, v151
	v_fmac_f32_e32 v88, v28, v152
	v_fmac_f32_e32 v90, v29, v153
	v_add_f32_e32 v84, v88, v90
	v_sub_f32_e32 v26, v26, v84
	ds_read_b128 v[150:153], v143 offset:10608
	s_waitcnt lgkmcnt(7)
	v_fma_f32 v88, v4, v114, 0
	v_fma_f32 v90, v5, v115, 0
	v_fmac_f32_e32 v88, v80, v116
	v_fmac_f32_e32 v90, v81, v117
	ds_read_b128 v[114:117], v143 offset:10624
	s_waitcnt lgkmcnt(7)
	v_fmac_f32_e32 v88, v82, v118
	v_fmac_f32_e32 v90, v83, v119
	v_fmac_f32_e32 v88, v60, v120
	v_fmac_f32_e32 v90, v61, v121
	ds_read_b128 v[118:121], v143 offset:10640
	s_waitcnt lgkmcnt(7)
	v_fmac_f32_e32 v88, v58, v122
	v_fmac_f32_e32 v90, v59, v123
	v_fmac_f32_e32 v88, v56, v124
	v_fmac_f32_e32 v90, v57, v125
	ds_read_b32 v122, v143 offset:10656
	s_waitcnt lgkmcnt(7)
	v_fmac_f32_e32 v88, v54, v126
	v_fmac_f32_e32 v90, v55, v127
	v_fmac_f32_e32 v88, v52, v128
	v_fmac_f32_e32 v90, v53, v129
	ds_read_b128 v[126:129], v143 offset:10752
	s_waitcnt lgkmcnt(7)
	v_fmac_f32_e32 v88, v50, v130
	v_fmac_f32_e32 v90, v51, v131
	v_fmac_f32_e32 v88, v48, v132
	v_fmac_f32_e32 v90, v49, v133
	ds_read_b128 v[130:133], v143 offset:10768
	s_waitcnt lgkmcnt(7)
	v_fmac_f32_e32 v88, v46, v134
	v_fmac_f32_e32 v90, v47, v135
	v_fmac_f32_e32 v88, v44, v136
	v_fmac_f32_e32 v90, v45, v137
	ds_read_b128 v[134:137], v143 offset:10784
	s_waitcnt lgkmcnt(7)
	v_fmac_f32_e32 v88, v42, v146
	v_fmac_f32_e32 v90, v43, v147
	v_fmac_f32_e32 v88, v40, v148
	v_fmac_f32_e32 v90, v41, v149
	ds_read_b128 v[146:149], v143 offset:10800
	s_waitcnt lgkmcnt(7)
	v_fmac_f32_e32 v88, v38, v150
	v_fmac_f32_e32 v90, v39, v151
	v_fmac_f32_e32 v88, v36, v152
	v_fmac_f32_e32 v90, v37, v153
	ds_read_b128 v[150:153], v143 offset:10816
	s_waitcnt lgkmcnt(7)
	v_fmac_f32_e32 v88, v34, v114
	v_fmac_f32_e32 v90, v35, v115
	v_fmac_f32_e32 v88, v32, v116
	v_fmac_f32_e32 v90, v33, v117
	ds_read_b128 v[114:117], v143 offset:10832
	s_waitcnt lgkmcnt(7)
	v_fmac_f32_e32 v88, v30, v118
	v_fmac_f32_e32 v90, v31, v119
	v_fmac_f32_e32 v88, v28, v120
	v_fmac_f32_e32 v90, v29, v121
	ds_read_b128 v[118:121], v143 offset:10848
	s_waitcnt lgkmcnt(7)
	v_fmac_f32_e32 v88, v26, v122
	v_add_f32_e32 v84, v90, v88
	v_sub_f32_e32 v27, v27, v84
	ds_read_b128 v[122:125], v143 offset:10864
	s_waitcnt lgkmcnt(7)
	v_fma_f32 v88, v4, v126, 0
	v_fma_f32 v90, v5, v127, 0
	v_fmac_f32_e32 v88, v80, v128
	v_fmac_f32_e32 v90, v81, v129
	ds_read_b128 v[126:129], v143 offset:10880
	s_waitcnt lgkmcnt(7)
	v_fmac_f32_e32 v88, v82, v130
	v_fmac_f32_e32 v90, v83, v131
	v_fmac_f32_e32 v88, v60, v132
	v_fmac_f32_e32 v90, v61, v133
	ds_read_b128 v[130:133], v143 offset:10896
	s_waitcnt lgkmcnt(7)
	v_fmac_f32_e32 v88, v58, v134
	v_fmac_f32_e32 v90, v59, v135
	v_fmac_f32_e32 v88, v56, v136
	v_fmac_f32_e32 v90, v57, v137
	ds_read_b64 v[134:135], v143 offset:10912
	s_waitcnt lgkmcnt(7)
	v_fmac_f32_e32 v88, v54, v146
	v_fmac_f32_e32 v90, v55, v147
	v_fmac_f32_e32 v88, v52, v148
	v_fmac_f32_e32 v90, v53, v149
	ds_read_b128 v[146:149], v143 offset:11008
	s_waitcnt lgkmcnt(7)
	v_fmac_f32_e32 v88, v50, v150
	v_fmac_f32_e32 v90, v51, v151
	v_fmac_f32_e32 v88, v48, v152
	v_fmac_f32_e32 v90, v49, v153
	ds_read_b128 v[150:153], v143 offset:11024
	s_waitcnt lgkmcnt(7)
	v_fmac_f32_e32 v88, v46, v114
	v_fmac_f32_e32 v90, v47, v115
	v_fmac_f32_e32 v88, v44, v116
	v_fmac_f32_e32 v90, v45, v117
	ds_read_b128 v[114:117], v143 offset:11040
	s_waitcnt lgkmcnt(7)
	v_fmac_f32_e32 v88, v42, v118
	v_fmac_f32_e32 v90, v43, v119
	v_fmac_f32_e32 v88, v40, v120
	v_fmac_f32_e32 v90, v41, v121
	ds_read_b128 v[118:121], v143 offset:11056
	s_waitcnt lgkmcnt(7)
; DI void gdn_g1(const Params& p, int l, int ch, char* smem) {
;     ...
;     for (int cc = 1; cc < 64; ++cc) { float a0 = 0.f, a1 = 0.f;
; #pragma unroll
;       for (int s2 = 0; s2 < cc; ++s2) { if (s2 & 1) a1 += sA[cc * 64 + s2] * sol[s2]; else a0 += sA[cc * 64 + s2] * sol[s2]; }
;       sol[cc] -= a0 + a1; }
	v_fmac_f32_e32 v88, v38, v122
	v_fmac_f32_e32 v90, v39, v123
	v_fmac_f32_e32 v88, v36, v124
	v_fmac_f32_e32 v90, v37, v125
	ds_read_b128 v[122:125], v143 offset:11072
	s_waitcnt lgkmcnt(7)
	v_fmac_f32_e32 v88, v34, v126
	v_fmac_f32_e32 v90, v35, v127
	v_fmac_f32_e32 v88, v32, v128
	v_fmac_f32_e32 v90, v33, v129
	ds_read_b128 v[126:129], v143 offset:11088
	s_waitcnt lgkmcnt(7)
	v_fmac_f32_e32 v88, v30, v130
	v_fmac_f32_e32 v90, v31, v131
	v_fmac_f32_e32 v88, v28, v132
	v_fmac_f32_e32 v90, v29, v133
	ds_read_b128 v[130:133], v143 offset:11104
	s_waitcnt lgkmcnt(7)
	v_fmac_f32_e32 v88, v26, v134
	v_fmac_f32_e32 v90, v27, v135
	v_add_f32_e32 v84, v88, v90
	v_sub_f32_e32 v24, v24, v84
	ds_read_b128 v[134:137], v143 offset:11120
	s_waitcnt lgkmcnt(7)
	v_fma_f32 v88, v4, v146, 0
	v_fma_f32 v90, v5, v147, 0
	v_fmac_f32_e32 v88, v80, v148
	v_fmac_f32_e32 v90, v81, v149
	ds_read_b128 v[146:149], v143 offset:11136
	s_waitcnt lgkmcnt(7)
	v_fmac_f32_e32 v88, v82, v150
	v_fmac_f32_e32 v90, v83, v151
	v_fmac_f32_e32 v88, v60, v152
	v_fmac_f32_e32 v90, v61, v153
	ds_read_b128 v[150:153], v143 offset:11152
	s_waitcnt lgkmcnt(7)
	v_fmac_f32_e32 v88, v58, v114
	v_fmac_f32_e32 v90, v59, v115
	v_fmac_f32_e32 v88, v56, v116
	v_fmac_f32_e32 v90, v57, v117
	ds_read_b96 v[114:116], v143 offset:11168
	s_waitcnt lgkmcnt(7)
	v_fmac_f32_e32 v88, v54, v118
	v_fmac_f32_e32 v90, v55, v119
	v_fmac_f32_e32 v88, v52, v120
	v_fmac_f32_e32 v90, v53, v121
	ds_read_b128 v[118:121], v143 offset:11264
	s_waitcnt lgkmcnt(7)
	v_fmac_f32_e32 v88, v50, v122
	v_fmac_f32_e32 v90, v51, v123
	v_fmac_f32_e32 v88, v48, v124
	v_fmac_f32_e32 v90, v49, v125
	ds_read_b128 v[122:125], v143 offset:11280
	s_waitcnt lgkmcnt(7)
	v_fmac_f32_e32 v88, v46, v126
	v_fmac_f32_e32 v90, v47, v127
	v_fmac_f32_e32 v88, v44, v128
	v_fmac_f32_e32 v90, v45, v129
	ds_read_b128 v[126:129], v143 offset:11296
	s_waitcnt lgkmcnt(7)
	v_fmac_f32_e32 v88, v42, v130
	v_fmac_f32_e32 v90, v43, v131
	v_fmac_f32_e32 v88, v40, v132
	v_fmac_f32_e32 v90, v41, v133
	ds_read_b128 v[130:133], v143 offset:11312
	s_waitcnt lgkmcnt(7)
	v_fmac_f32_e32 v88, v38, v134
	v_fmac_f32_e32 v90, v39, v135
	v_fmac_f32_e32 v88, v36, v136
	v_fmac_f32_e32 v90, v37, v137
	ds_read_b128 v[134:137], v143 offset:11328
	s_waitcnt lgkmcnt(7)
	v_fmac_f32_e32 v88, v34, v146
	v_fmac_f32_e32 v90, v35, v147
	v_fmac_f32_e32 v88, v32, v148
	v_fmac_f32_e32 v90, v33, v149
	ds_read_b128 v[146:149], v143 offset:11344
	s_waitcnt lgkmcnt(7)
	v_fmac_f32_e32 v88, v30, v150
	v_fmac_f32_e32 v90, v31, v151
	v_fmac_f32_e32 v88, v28, v152
	v_fmac_f32_e32 v90, v29, v153
	ds_read_b128 v[150:153], v143 offset:11360
	s_waitcnt lgkmcnt(7)
	v_fmac_f32_e32 v88, v26, v114
	v_fmac_f32_e32 v90, v27, v115
	v_fmac_f32_e32 v88, v24, v116
	v_add_f32_e32 v84, v90, v88
	v_sub_f32_e32 v25, v25, v84
	ds_read_b128 v[114:117], v143 offset:11376
	s_waitcnt lgkmcnt(7)
	v_fma_f32 v88, v4, v118, 0
	v_fma_f32 v90, v5, v119, 0
	v_fmac_f32_e32 v88, v80, v120
	v_fmac_f32_e32 v90, v81, v121
	ds_read_b128 v[118:121], v143 offset:11392
	s_waitcnt lgkmcnt(7)
	v_fmac_f32_e32 v88, v82, v122
	v_fmac_f32_e32 v90, v83, v123
	v_fmac_f32_e32 v88, v60, v124
	v_fmac_f32_e32 v90, v61, v125
	ds_read_b128 v[122:125], v143 offset:11408
	s_waitcnt lgkmcnt(7)
	v_fmac_f32_e32 v88, v58, v126
	v_fmac_f32_e32 v90, v59, v127
	v_fmac_f32_e32 v88, v56, v128
	v_fmac_f32_e32 v90, v57, v129
	ds_read_b128 v[126:129], v143 offset:11424
	s_waitcnt lgkmcnt(7)
	v_fmac_f32_e32 v88, v54, v130
	v_fmac_f32_e32 v90, v55, v131
	v_fmac_f32_e32 v88, v52, v132
	v_fmac_f32_e32 v90, v53, v133
	ds_read_b128 v[130:133], v143 offset:11520
	s_waitcnt lgkmcnt(7)
	v_fmac_f32_e32 v88, v50, v134
	v_fmac_f32_e32 v90, v51, v135
	v_fmac_f32_e32 v88, v48, v136
	v_fmac_f32_e32 v90, v49, v137
	ds_read_b128 v[134:137], v143 offset:11536
	s_waitcnt lgkmcnt(7)
	v_fmac_f32_e32 v88, v46, v146
	v_fmac_f32_e32 v90, v47, v147
	v_fmac_f32_e32 v88, v44, v148
	v_fmac_f32_e32 v90, v45, v149
	ds_read_b128 v[146:149], v143 offset:11552
	s_waitcnt lgkmcnt(7)
	v_fmac_f32_e32 v88, v42, v150
	v_fmac_f32_e32 v90, v43, v151
	v_fmac_f32_e32 v88, v40, v152
	v_fmac_f32_e32 v90, v41, v153
	ds_read_b128 v[150:153], v143 offset:11568
	s_waitcnt lgkmcnt(7)
	v_fmac_f32_e32 v88, v38, v114
	v_fmac_f32_e32 v90, v39, v115
	v_fmac_f32_e32 v88, v36, v116
	v_fmac_f32_e32 v90, v37, v117
	ds_read_b128 v[114:117], v143 offset:11584
	s_waitcnt lgkmcnt(7)
	v_fmac_f32_e32 v88, v34, v118
	v_fmac_f32_e32 v90, v35, v119
	v_fmac_f32_e32 v88, v32, v120
	v_fmac_f32_e32 v90, v33, v121
	ds_read_b128 v[118:121], v143 offset:11600
	s_waitcnt lgkmcnt(7)
	v_fmac_f32_e32 v88, v30, v122
	v_fmac_f32_e32 v90, v31, v123
	v_fmac_f32_e32 v88, v28, v124
	v_fmac_f32_e32 v90, v29, v125
	ds_read_b128 v[122:125], v143 offset:11616
	s_waitcnt lgkmcnt(7)
	v_fmac_f32_e32 v88, v26, v126
	v_fmac_f32_e32 v90, v27, v127
	v_fmac_f32_e32 v88, v24, v128
	v_fmac_f32_e32 v90, v25, v129
	v_add_f32_e32 v84, v88, v90
	v_sub_f32_e32 v22, v22, v84
	ds_read_b128 v[126:129], v143 offset:11632
	s_waitcnt lgkmcnt(7)
	v_fma_f32 v88, v4, v130, 0
	v_fma_f32 v90, v5, v131, 0
	v_fmac_f32_e32 v88, v80, v132
	v_fmac_f32_e32 v90, v81, v133
	ds_read_b128 v[130:133], v143 offset:11648
	s_waitcnt lgkmcnt(7)
	v_fmac_f32_e32 v88, v82, v134
	v_fmac_f32_e32 v90, v83, v135
	v_fmac_f32_e32 v88, v60, v136
	v_fmac_f32_e32 v90, v61, v137
	ds_read_b128 v[134:137], v143 offset:11664
	s_waitcnt lgkmcnt(7)
	v_fmac_f32_e32 v88, v58, v146
	v_fmac_f32_e32 v90, v59, v147
	v_fmac_f32_e32 v88, v56, v148
	v_fmac_f32_e32 v90, v57, v149
	ds_read_b128 v[146:149], v143 offset:11680
	s_waitcnt lgkmcnt(7)
; DI void gdn_g1(const Params& p, int l, int ch, char* smem) {
;     ...
;     for (int cc = 1; cc < 64; ++cc) { float a0 = 0.f, a1 = 0.f;
; #pragma unroll
;       for (int s2 = 0; s2 < cc; ++s2) { if (s2 & 1) a1 += sA[cc * 64 + s2] * sol[s2]; else a0 += sA[cc * 64 + s2] * sol[s2]; }
;       sol[cc] -= a0 + a1; }
	v_fmac_f32_e32 v88, v54, v150
	v_fmac_f32_e32 v90, v55, v151
	v_fmac_f32_e32 v88, v52, v152
	v_fmac_f32_e32 v90, v53, v153
	ds_read_b32 v150, v143 offset:11696
	s_waitcnt lgkmcnt(7)
	v_fmac_f32_e32 v88, v50, v114
	v_fmac_f32_e32 v90, v51, v115
	v_fmac_f32_e32 v88, v48, v116
	v_fmac_f32_e32 v90, v49, v117
	ds_read_b128 v[114:117], v143 offset:11776
	s_waitcnt lgkmcnt(7)
	v_fmac_f32_e32 v88, v46, v118
	v_fmac_f32_e32 v90, v47, v119
	v_fmac_f32_e32 v88, v44, v120
	v_fmac_f32_e32 v90, v45, v121
	ds_read_b128 v[118:121], v143 offset:11792
	s_waitcnt lgkmcnt(7)
	v_fmac_f32_e32 v88, v42, v122
	v_fmac_f32_e32 v90, v43, v123
	v_fmac_f32_e32 v88, v40, v124
	v_fmac_f32_e32 v90, v41, v125
	ds_read_b128 v[122:125], v143 offset:11808
	s_waitcnt lgkmcnt(7)
	v_fmac_f32_e32 v88, v38, v126
	v_fmac_f32_e32 v90, v39, v127
	v_fmac_f32_e32 v88, v36, v128
	v_fmac_f32_e32 v90, v37, v129
	ds_read_b128 v[126:129], v143 offset:11824
	s_waitcnt lgkmcnt(7)
	v_fmac_f32_e32 v88, v34, v130
	v_fmac_f32_e32 v90, v35, v131
	v_fmac_f32_e32 v88, v32, v132
	v_fmac_f32_e32 v90, v33, v133
	ds_read_b128 v[130:133], v143 offset:11840
	s_waitcnt lgkmcnt(7)
	v_fmac_f32_e32 v88, v30, v134
	v_fmac_f32_e32 v90, v31, v135
	v_fmac_f32_e32 v88, v28, v136
	v_fmac_f32_e32 v90, v29, v137
	ds_read_b128 v[134:137], v143 offset:11856
	s_waitcnt lgkmcnt(7)
	v_fmac_f32_e32 v88, v26, v146
	v_fmac_f32_e32 v90, v27, v147
	v_fmac_f32_e32 v88, v24, v148
	v_fmac_f32_e32 v90, v25, v149
	ds_read_b128 v[146:149], v143 offset:11872
	s_waitcnt lgkmcnt(7)
	v_fmac_f32_e32 v88, v22, v150
	v_add_f32_e32 v84, v90, v88
	v_sub_f32_e32 v23, v23, v84
	ds_read_b128 v[150:153], v143 offset:11888
	s_waitcnt lgkmcnt(7)
	v_fma_f32 v88, v4, v114, 0
	v_fma_f32 v90, v5, v115, 0
	v_fmac_f32_e32 v88, v80, v116
	v_fmac_f32_e32 v90, v81, v117
	ds_read_b128 v[114:117], v143 offset:11904
	s_waitcnt lgkmcnt(7)
	v_fmac_f32_e32 v88, v82, v118
	v_fmac_f32_e32 v90, v83, v119
	v_fmac_f32_e32 v88, v60, v120
	v_fmac_f32_e32 v90, v61, v121
	ds_read_b128 v[118:121], v143 offset:11920
	s_waitcnt lgkmcnt(7)
	v_fmac_f32_e32 v88, v58, v122
	v_fmac_f32_e32 v90, v59, v123
	v_fmac_f32_e32 v88, v56, v124
	v_fmac_f32_e32 v90, v57, v125
	ds_read_b128 v[122:125], v143 offset:11936
	s_waitcnt lgkmcnt(7)
	v_fmac_f32_e32 v88, v54, v126
	v_fmac_f32_e32 v90, v55, v127
	v_fmac_f32_e32 v88, v52, v128
	v_fmac_f32_e32 v90, v53, v129
	ds_read_b64 v[126:127], v143 offset:11952
	s_waitcnt lgkmcnt(7)
	v_fmac_f32_e32 v88, v50, v130
	v_fmac_f32_e32 v90, v51, v131
	v_fmac_f32_e32 v88, v48, v132
	v_fmac_f32_e32 v90, v49, v133
	ds_read_b128 v[130:133], v143 offset:12032
	s_waitcnt lgkmcnt(7)
	v_fmac_f32_e32 v88, v46, v134
	v_fmac_f32_e32 v90, v47, v135
	v_fmac_f32_e32 v88, v44, v136
	v_fmac_f32_e32 v90, v45, v137
	ds_read_b128 v[134:137], v143 offset:12048
	s_waitcnt lgkmcnt(7)
	v_fmac_f32_e32 v88, v42, v146
	v_fmac_f32_e32 v90, v43, v147
	v_fmac_f32_e32 v88, v40, v148
	v_fmac_f32_e32 v90, v41, v149
	ds_read_b128 v[146:149], v143 offset:12064
	s_waitcnt lgkmcnt(7)
	v_fmac_f32_e32 v88, v38, v150
	v_fmac_f32_e32 v90, v39, v151
	v_fmac_f32_e32 v88, v36, v152
	v_fmac_f32_e32 v90, v37, v153
	ds_read_b128 v[150:153], v143 offset:12080
	s_waitcnt lgkmcnt(7)
	v_fmac_f32_e32 v88, v34, v114
	v_fmac_f32_e32 v90, v35, v115
	v_fmac_f32_e32 v88, v32, v116
	v_fmac_f32_e32 v90, v33, v117
	ds_read_b128 v[114:117], v143 offset:12096
	s_waitcnt lgkmcnt(7)
	v_fmac_f32_e32 v88, v30, v118
	v_fmac_f32_e32 v90, v31, v119
	v_fmac_f32_e32 v88, v28, v120
	v_fmac_f32_e32 v90, v29, v121
	ds_read_b128 v[118:121], v143 offset:12112
	s_waitcnt lgkmcnt(7)
	v_fmac_f32_e32 v88, v26, v122
	v_fmac_f32_e32 v90, v27, v123
	v_fmac_f32_e32 v88, v24, v124
	v_fmac_f32_e32 v90, v25, v125
	ds_read_b128 v[122:125], v143 offset:12128
	s_waitcnt lgkmcnt(7)
	v_fmac_f32_e32 v88, v22, v126
	v_fmac_f32_e32 v90, v23, v127
	v_add_f32_e32 v84, v88, v90
	v_sub_f32_e32 v20, v20, v84
	ds_read_b128 v[126:129], v143 offset:12144
	s_waitcnt lgkmcnt(7)
	v_fma_f32 v88, v4, v130, 0
	v_fma_f32 v90, v5, v131, 0
	v_fmac_f32_e32 v88, v80, v132
	v_fmac_f32_e32 v90, v81, v133
	ds_read_b128 v[130:133], v143 offset:12160
	s_waitcnt lgkmcnt(7)
	v_fmac_f32_e32 v88, v82, v134
	v_fmac_f32_e32 v90, v83, v135
	v_fmac_f32_e32 v88, v60, v136
	v_fmac_f32_e32 v90, v61, v137
	ds_read_b128 v[134:137], v143 offset:12176
	s_waitcnt lgkmcnt(7)
	v_fmac_f32_e32 v88, v58, v146
	v_fmac_f32_e32 v90, v59, v147
	v_fmac_f32_e32 v88, v56, v148
	v_fmac_f32_e32 v90, v57, v149
	ds_read_b128 v[146:149], v143 offset:12192
	s_waitcnt lgkmcnt(7)
	v_fmac_f32_e32 v88, v54, v150
	v_fmac_f32_e32 v90, v55, v151
	v_fmac_f32_e32 v88, v52, v152
	v_fmac_f32_e32 v90, v53, v153
	ds_read_b96 v[150:152], v143 offset:12208
	s_waitcnt lgkmcnt(7)
	v_fmac_f32_e32 v88, v50, v114
	v_fmac_f32_e32 v90, v51, v115
	v_fmac_f32_e32 v88, v48, v116
	v_fmac_f32_e32 v90, v49, v117
	ds_read_b128 v[114:117], v143 offset:12288
	s_waitcnt lgkmcnt(7)
	v_fmac_f32_e32 v88, v46, v118
	v_fmac_f32_e32 v90, v47, v119
	v_fmac_f32_e32 v88, v44, v120
	v_fmac_f32_e32 v90, v45, v121
	ds_read_b128 v[118:121], v143 offset:12304
	s_waitcnt lgkmcnt(7)
	v_fmac_f32_e32 v88, v42, v122
	v_fmac_f32_e32 v90, v43, v123
	v_fmac_f32_e32 v88, v40, v124
	v_fmac_f32_e32 v90, v41, v125
	ds_read_b128 v[122:125], v143 offset:12320
	s_waitcnt lgkmcnt(7)
	v_fmac_f32_e32 v88, v38, v126
	v_fmac_f32_e32 v90, v39, v127
	v_fmac_f32_e32 v88, v36, v128
	v_fmac_f32_e32 v90, v37, v129
	ds_read_b128 v[126:129], v143 offset:12336
	s_waitcnt lgkmcnt(7)
	v_fmac_f32_e32 v88, v34, v130
	v_fmac_f32_e32 v90, v35, v131
	v_fmac_f32_e32 v88, v32, v132
	v_fmac_f32_e32 v90, v33, v133
	ds_read_b128 v[130:133], v143 offset:12352
	s_waitcnt lgkmcnt(7)
; DI void gdn_g1(const Params& p, int l, int ch, char* smem) {
;     ...
;     for (int cc = 1; cc < 64; ++cc) { float a0 = 0.f, a1 = 0.f;
; #pragma unroll
;       for (int s2 = 0; s2 < cc; ++s2) { if (s2 & 1) a1 += sA[cc * 64 + s2] * sol[s2]; else a0 += sA[cc * 64 + s2] * sol[s2]; }
;       sol[cc] -= a0 + a1; }
	v_fmac_f32_e32 v88, v30, v134
	v_fmac_f32_e32 v90, v31, v135
	v_fmac_f32_e32 v88, v28, v136
	v_fmac_f32_e32 v90, v29, v137
	ds_read_b128 v[134:137], v143 offset:12368
	s_waitcnt lgkmcnt(7)
	v_fmac_f32_e32 v88, v26, v146
	v_fmac_f32_e32 v90, v27, v147
	v_fmac_f32_e32 v88, v24, v148
	v_fmac_f32_e32 v90, v25, v149
	ds_read_b128 v[146:149], v143 offset:12384
	s_waitcnt lgkmcnt(7)
	v_fmac_f32_e32 v88, v22, v150
	v_fmac_f32_e32 v90, v23, v151
	v_fmac_f32_e32 v88, v20, v152
	v_add_f32_e32 v84, v90, v88
	v_sub_f32_e32 v21, v21, v84
	ds_read_b128 v[150:153], v143 offset:12400
	s_waitcnt lgkmcnt(7)
	v_fma_f32 v88, v4, v114, 0
	v_fma_f32 v90, v5, v115, 0
	v_fmac_f32_e32 v88, v80, v116
	v_fmac_f32_e32 v90, v81, v117
	ds_read_b128 v[114:117], v143 offset:12416
	s_waitcnt lgkmcnt(7)
	v_fmac_f32_e32 v88, v82, v118
	v_fmac_f32_e32 v90, v83, v119
	v_fmac_f32_e32 v88, v60, v120
	v_fmac_f32_e32 v90, v61, v121
	ds_read_b128 v[118:121], v143 offset:12432
	s_waitcnt lgkmcnt(7)
	v_fmac_f32_e32 v88, v58, v122
	v_fmac_f32_e32 v90, v59, v123
	v_fmac_f32_e32 v88, v56, v124
	v_fmac_f32_e32 v90, v57, v125
	ds_read_b128 v[122:125], v143 offset:12448
	s_waitcnt lgkmcnt(7)
	v_fmac_f32_e32 v88, v54, v126
	v_fmac_f32_e32 v90, v55, v127
	v_fmac_f32_e32 v88, v52, v128
	v_fmac_f32_e32 v90, v53, v129
	ds_read_b128 v[126:129], v143 offset:12464
	s_waitcnt lgkmcnt(7)
	v_fmac_f32_e32 v88, v50, v130
	v_fmac_f32_e32 v90, v51, v131
	v_fmac_f32_e32 v88, v48, v132
	v_fmac_f32_e32 v90, v49, v133
	ds_read_b128 v[130:133], v143 offset:12544
	s_waitcnt lgkmcnt(7)
	v_fmac_f32_e32 v88, v46, v134
	v_fmac_f32_e32 v90, v47, v135
	v_fmac_f32_e32 v88, v44, v136
	v_fmac_f32_e32 v90, v45, v137
	ds_read_b128 v[134:137], v143 offset:12560
	s_waitcnt lgkmcnt(7)
	v_fmac_f32_e32 v88, v42, v146
	v_fmac_f32_e32 v90, v43, v147
	v_fmac_f32_e32 v88, v40, v148
	v_fmac_f32_e32 v90, v41, v149
	ds_read_b128 v[146:149], v143 offset:12576
	s_waitcnt lgkmcnt(7)
	v_fmac_f32_e32 v88, v38, v150
	v_fmac_f32_e32 v90, v39, v151
	v_fmac_f32_e32 v88, v36, v152
	v_fmac_f32_e32 v90, v37, v153
	ds_read_b128 v[150:153], v143 offset:12592
	s_waitcnt lgkmcnt(7)
	v_fmac_f32_e32 v88, v34, v114
	v_fmac_f32_e32 v90, v35, v115
	v_fmac_f32_e32 v88, v32, v116
	v_fmac_f32_e32 v90, v33, v117
	ds_read_b128 v[114:117], v143 offset:12608
	s_waitcnt lgkmcnt(7)
	v_fmac_f32_e32 v88, v30, v118
	v_fmac_f32_e32 v90, v31, v119
	v_fmac_f32_e32 v88, v28, v120
	v_fmac_f32_e32 v90, v29, v121
	ds_read_b128 v[118:121], v143 offset:12624
	s_waitcnt lgkmcnt(7)
	v_fmac_f32_e32 v88, v26, v122
	v_fmac_f32_e32 v90, v27, v123
	v_fmac_f32_e32 v88, v24, v124
	v_fmac_f32_e32 v90, v25, v125
	ds_read_b128 v[122:125], v143 offset:12640
	s_waitcnt lgkmcnt(7)
	v_fmac_f32_e32 v88, v22, v126
	v_fmac_f32_e32 v90, v23, v127
	v_fmac_f32_e32 v88, v20, v128
	v_fmac_f32_e32 v90, v21, v129
	v_add_f32_e32 v84, v88, v90
	v_sub_f32_e32 v18, v18, v84
	ds_read_b128 v[126:129], v143 offset:12656
	s_waitcnt lgkmcnt(7)
	v_fma_f32 v88, v4, v130, 0
	v_fma_f32 v90, v5, v131, 0
	v_fmac_f32_e32 v88, v80, v132
	v_fmac_f32_e32 v90, v81, v133
	ds_read_b128 v[130:133], v143 offset:12672
	s_waitcnt lgkmcnt(7)
	v_fmac_f32_e32 v88, v82, v134
	v_fmac_f32_e32 v90, v83, v135
	v_fmac_f32_e32 v88, v60, v136
	v_fmac_f32_e32 v90, v61, v137
	ds_read_b128 v[134:137], v143 offset:12688
	s_waitcnt lgkmcnt(7)
	v_fmac_f32_e32 v88, v58, v146
	v_fmac_f32_e32 v90, v59, v147
	v_fmac_f32_e32 v88, v56, v148
	v_fmac_f32_e32 v90, v57, v149
	ds_read_b128 v[146:149], v143 offset:12704
	s_waitcnt lgkmcnt(7)
	v_fmac_f32_e32 v88, v54, v150
	v_fmac_f32_e32 v90, v55, v151
	v_fmac_f32_e32 v88, v52, v152
	v_fmac_f32_e32 v90, v53, v153
	ds_read_b128 v[150:153], v143 offset:12720
	s_waitcnt lgkmcnt(7)
	v_fmac_f32_e32 v88, v50, v114
	v_fmac_f32_e32 v90, v51, v115
	v_fmac_f32_e32 v88, v48, v116
	v_fmac_f32_e32 v90, v49, v117
	ds_read_b32 v114, v143 offset:12736
	s_waitcnt lgkmcnt(7)
	v_fmac_f32_e32 v88, v46, v118
	v_fmac_f32_e32 v90, v47, v119
	v_fmac_f32_e32 v88, v44, v120
	v_fmac_f32_e32 v90, v45, v121
	ds_read_b128 v[118:121], v143 offset:12800
	s_waitcnt lgkmcnt(7)
	v_fmac_f32_e32 v88, v42, v122
	v_fmac_f32_e32 v90, v43, v123
	v_fmac_f32_e32 v88, v40, v124
	v_fmac_f32_e32 v90, v41, v125
	ds_read_b128 v[122:125], v143 offset:12816
	s_waitcnt lgkmcnt(7)
	v_fmac_f32_e32 v88, v38, v126
	v_fmac_f32_e32 v90, v39, v127
	v_fmac_f32_e32 v88, v36, v128
	v_fmac_f32_e32 v90, v37, v129
	ds_read_b128 v[126:129], v143 offset:12832
	s_waitcnt lgkmcnt(7)
	v_fmac_f32_e32 v88, v34, v130
	v_fmac_f32_e32 v90, v35, v131
	v_fmac_f32_e32 v88, v32, v132
	v_fmac_f32_e32 v90, v33, v133
	ds_read_b128 v[130:133], v143 offset:12848
	s_waitcnt lgkmcnt(7)
	v_fmac_f32_e32 v88, v30, v134
	v_fmac_f32_e32 v90, v31, v135
	v_fmac_f32_e32 v88, v28, v136
	v_fmac_f32_e32 v90, v29, v137
	ds_read_b128 v[134:137], v143 offset:12864
	s_waitcnt lgkmcnt(7)
	v_fmac_f32_e32 v88, v26, v146
	v_fmac_f32_e32 v90, v27, v147
	v_fmac_f32_e32 v88, v24, v148
	v_fmac_f32_e32 v90, v25, v149
	ds_read_b128 v[146:149], v143 offset:12880
	s_waitcnt lgkmcnt(7)
	v_fmac_f32_e32 v88, v22, v150
	v_fmac_f32_e32 v90, v23, v151
	v_fmac_f32_e32 v88, v20, v152
	v_fmac_f32_e32 v90, v21, v153
	ds_read_b128 v[150:153], v143 offset:12896
	s_waitcnt lgkmcnt(7)
	v_fmac_f32_e32 v88, v18, v114
	v_add_f32_e32 v84, v90, v88
	v_sub_f32_e32 v19, v19, v84
	ds_read_b128 v[114:117], v143 offset:12912
	s_waitcnt lgkmcnt(7)
	v_fma_f32 v88, v4, v118, 0
	v_fma_f32 v90, v5, v119, 0
	v_fmac_f32_e32 v88, v80, v120
	v_fmac_f32_e32 v90, v81, v121
	ds_read_b128 v[118:121], v143 offset:12928
	s_waitcnt lgkmcnt(7)
	v_fmac_f32_e32 v88, v82, v122
	v_fmac_f32_e32 v90, v83, v123
	v_fmac_f32_e32 v88, v60, v124
	v_fmac_f32_e32 v90, v61, v125
	ds_read_b128 v[122:125], v143 offset:12944
	s_waitcnt lgkmcnt(7)
; DI void gdn_g1(const Params& p, int l, int ch, char* smem) {
;     ...
;     for (int cc = 1; cc < 64; ++cc) { float a0 = 0.f, a1 = 0.f;
; #pragma unroll
;       for (int s2 = 0; s2 < cc; ++s2) { if (s2 & 1) a1 += sA[cc * 64 + s2] * sol[s2]; else a0 += sA[cc * 64 + s2] * sol[s2]; }
;       sol[cc] -= a0 + a1; }
	v_fmac_f32_e32 v88, v58, v126
	v_fmac_f32_e32 v90, v59, v127
	v_fmac_f32_e32 v88, v56, v128
	v_fmac_f32_e32 v90, v57, v129
	ds_read_b128 v[126:129], v143 offset:12960
	s_waitcnt lgkmcnt(7)
	v_fmac_f32_e32 v88, v54, v130
	v_fmac_f32_e32 v90, v55, v131
	v_fmac_f32_e32 v88, v52, v132
	v_fmac_f32_e32 v90, v53, v133
	ds_read_b128 v[130:133], v143 offset:12976
	s_waitcnt lgkmcnt(7)
	v_fmac_f32_e32 v88, v50, v134
	v_fmac_f32_e32 v90, v51, v135
	v_fmac_f32_e32 v88, v48, v136
	v_fmac_f32_e32 v90, v49, v137
	ds_read_b64 v[134:135], v143 offset:12992
	s_waitcnt lgkmcnt(7)
	v_fmac_f32_e32 v88, v46, v146
	v_fmac_f32_e32 v90, v47, v147
	v_fmac_f32_e32 v88, v44, v148
	v_fmac_f32_e32 v90, v45, v149
	ds_read_b128 v[146:149], v143 offset:13056
	s_waitcnt lgkmcnt(7)
	v_fmac_f32_e32 v88, v42, v150
	v_fmac_f32_e32 v90, v43, v151
	v_fmac_f32_e32 v88, v40, v152
	v_fmac_f32_e32 v90, v41, v153
	ds_read_b128 v[150:153], v143 offset:13072
	s_waitcnt lgkmcnt(7)
	v_fmac_f32_e32 v88, v38, v114
	v_fmac_f32_e32 v90, v39, v115
	v_fmac_f32_e32 v88, v36, v116
	v_fmac_f32_e32 v90, v37, v117
	ds_read_b128 v[114:117], v143 offset:13088
	s_waitcnt lgkmcnt(7)
	v_fmac_f32_e32 v88, v34, v118
	v_fmac_f32_e32 v90, v35, v119
	v_fmac_f32_e32 v88, v32, v120
	v_fmac_f32_e32 v90, v33, v121
	ds_read_b128 v[118:121], v143 offset:13104
	s_waitcnt lgkmcnt(7)
	v_fmac_f32_e32 v88, v30, v122
	v_fmac_f32_e32 v90, v31, v123
	v_fmac_f32_e32 v88, v28, v124
	v_fmac_f32_e32 v90, v29, v125
	ds_read_b128 v[122:125], v143 offset:13120
	s_waitcnt lgkmcnt(7)
	v_fmac_f32_e32 v88, v26, v126
	v_fmac_f32_e32 v90, v27, v127
	v_fmac_f32_e32 v88, v24, v128
	v_fmac_f32_e32 v90, v25, v129
	ds_read_b128 v[126:129], v143 offset:13136
	s_waitcnt lgkmcnt(7)
	v_fmac_f32_e32 v88, v22, v130
	v_fmac_f32_e32 v90, v23, v131
	v_fmac_f32_e32 v88, v20, v132
	v_fmac_f32_e32 v90, v21, v133
	ds_read_b128 v[130:133], v143 offset:13152
	s_waitcnt lgkmcnt(7)
	v_fmac_f32_e32 v88, v18, v134
	v_fmac_f32_e32 v90, v19, v135
	v_add_f32_e32 v84, v88, v90
	v_sub_f32_e32 v16, v16, v84
	ds_read_b128 v[134:137], v143 offset:13168
	s_waitcnt lgkmcnt(7)
	v_fma_f32 v88, v4, v146, 0
	v_fma_f32 v90, v5, v147, 0
	v_fmac_f32_e32 v88, v80, v148
	v_fmac_f32_e32 v90, v81, v149
	ds_read_b128 v[146:149], v143 offset:13184
	s_waitcnt lgkmcnt(7)
	v_fmac_f32_e32 v88, v82, v150
	v_fmac_f32_e32 v90, v83, v151
	v_fmac_f32_e32 v88, v60, v152
	v_fmac_f32_e32 v90, v61, v153
	ds_read_b128 v[150:153], v143 offset:13200
	s_waitcnt lgkmcnt(7)
	v_fmac_f32_e32 v88, v58, v114
	v_fmac_f32_e32 v90, v59, v115
	v_fmac_f32_e32 v88, v56, v116
	v_fmac_f32_e32 v90, v57, v117
	ds_read_b128 v[114:117], v143 offset:13216
	s_waitcnt lgkmcnt(7)
	v_fmac_f32_e32 v88, v54, v118
	v_fmac_f32_e32 v90, v55, v119
	v_fmac_f32_e32 v88, v52, v120
	v_fmac_f32_e32 v90, v53, v121
	ds_read_b128 v[118:121], v143 offset:13232
	s_waitcnt lgkmcnt(7)
	v_fmac_f32_e32 v88, v50, v122
	v_fmac_f32_e32 v90, v51, v123
	v_fmac_f32_e32 v88, v48, v124
	v_fmac_f32_e32 v90, v49, v125
	ds_read_b96 v[122:124], v143 offset:13248
	s_waitcnt lgkmcnt(7)
	v_fmac_f32_e32 v88, v46, v126
	v_fmac_f32_e32 v90, v47, v127
	v_fmac_f32_e32 v88, v44, v128
	v_fmac_f32_e32 v90, v45, v129
	ds_read_b128 v[126:129], v143 offset:13312
	s_waitcnt lgkmcnt(7)
	v_fmac_f32_e32 v88, v42, v130
	v_fmac_f32_e32 v90, v43, v131
	v_fmac_f32_e32 v88, v40, v132
	v_fmac_f32_e32 v90, v41, v133
	ds_read_b128 v[130:133], v143 offset:13328
	s_waitcnt lgkmcnt(7)
	v_fmac_f32_e32 v88, v38, v134
	v_fmac_f32_e32 v90, v39, v135
	v_fmac_f32_e32 v88, v36, v136
	v_fmac_f32_e32 v90, v37, v137
	ds_read_b128 v[134:137], v143 offset:13344
	s_waitcnt lgkmcnt(7)
	v_fmac_f32_e32 v88, v34, v146
	v_fmac_f32_e32 v90, v35, v147
	v_fmac_f32_e32 v88, v32, v148
	v_fmac_f32_e32 v90, v33, v149
	ds_read_b128 v[146:149], v143 offset:13360
	s_waitcnt lgkmcnt(7)
	v_fmac_f32_e32 v88, v30, v150
	v_fmac_f32_e32 v90, v31, v151
	v_fmac_f32_e32 v88, v28, v152
	v_fmac_f32_e32 v90, v29, v153
	ds_read_b128 v[150:153], v143 offset:13376
	s_waitcnt lgkmcnt(7)
	v_fmac_f32_e32 v88, v26, v114
	v_fmac_f32_e32 v90, v27, v115
	v_fmac_f32_e32 v88, v24, v116
	v_fmac_f32_e32 v90, v25, v117
	ds_read_b128 v[114:117], v143 offset:13392
	s_waitcnt lgkmcnt(7)
	v_fmac_f32_e32 v88, v22, v118
	v_fmac_f32_e32 v90, v23, v119
	v_fmac_f32_e32 v88, v20, v120
	v_fmac_f32_e32 v90, v21, v121
	ds_read_b128 v[118:121], v143 offset:13408
	s_waitcnt lgkmcnt(7)
	v_fmac_f32_e32 v88, v18, v122
	v_fmac_f32_e32 v90, v19, v123
	v_fmac_f32_e32 v88, v16, v124
	v_add_f32_e32 v84, v90, v88
	v_sub_f32_e32 v17, v17, v84
	ds_read_b128 v[122:125], v143 offset:13424
	s_waitcnt lgkmcnt(7)
	v_fma_f32 v88, v4, v126, 0
	v_fma_f32 v90, v5, v127, 0
	v_fmac_f32_e32 v88, v80, v128
	v_fmac_f32_e32 v90, v81, v129
	ds_read_b128 v[126:129], v143 offset:13440
	s_waitcnt lgkmcnt(7)
	v_fmac_f32_e32 v88, v82, v130
	v_fmac_f32_e32 v90, v83, v131
	v_fmac_f32_e32 v88, v60, v132
	v_fmac_f32_e32 v90, v61, v133
	ds_read_b128 v[130:133], v143 offset:13456
	s_waitcnt lgkmcnt(7)
	v_fmac_f32_e32 v88, v58, v134
	v_fmac_f32_e32 v90, v59, v135
	v_fmac_f32_e32 v88, v56, v136
	v_fmac_f32_e32 v90, v57, v137
	ds_read_b128 v[134:137], v143 offset:13472
	s_waitcnt lgkmcnt(7)
	v_fmac_f32_e32 v88, v54, v146
	v_fmac_f32_e32 v90, v55, v147
	v_fmac_f32_e32 v88, v52, v148
	v_fmac_f32_e32 v90, v53, v149
	ds_read_b128 v[146:149], v143 offset:13488
	s_waitcnt lgkmcnt(7)
	v_fmac_f32_e32 v88, v50, v150
	v_fmac_f32_e32 v90, v51, v151
	v_fmac_f32_e32 v88, v48, v152
	v_fmac_f32_e32 v90, v49, v153
	ds_read_b128 v[150:153], v143 offset:13504
	s_waitcnt lgkmcnt(7)
	v_fmac_f32_e32 v88, v46, v114
	v_fmac_f32_e32 v90, v47, v115
	v_fmac_f32_e32 v88, v44, v116
	v_fmac_f32_e32 v90, v45, v117
	ds_read_b128 v[114:117], v143 offset:13568
	s_waitcnt lgkmcnt(7)
; DI void gdn_g1(const Params& p, int l, int ch, char* smem) {
;     ...
;     for (int cc = 1; cc < 64; ++cc) { float a0 = 0.f, a1 = 0.f;
; #pragma unroll
;       for (int s2 = 0; s2 < cc; ++s2) { if (s2 & 1) a1 += sA[cc * 64 + s2] * sol[s2]; else a0 += sA[cc * 64 + s2] * sol[s2]; }
;       sol[cc] -= a0 + a1; }
	v_fmac_f32_e32 v88, v42, v118
	v_fmac_f32_e32 v90, v43, v119
	v_fmac_f32_e32 v88, v40, v120
	v_fmac_f32_e32 v90, v41, v121
	ds_read_b128 v[118:121], v143 offset:13584
	s_waitcnt lgkmcnt(7)
	v_fmac_f32_e32 v88, v38, v122
	v_fmac_f32_e32 v90, v39, v123
	v_fmac_f32_e32 v88, v36, v124
	v_fmac_f32_e32 v90, v37, v125
	ds_read_b128 v[122:125], v143 offset:13600
	s_waitcnt lgkmcnt(7)
	v_fmac_f32_e32 v88, v34, v126
	v_fmac_f32_e32 v90, v35, v127
	v_fmac_f32_e32 v88, v32, v128
	v_fmac_f32_e32 v90, v33, v129
	ds_read_b128 v[126:129], v143 offset:13616
	s_waitcnt lgkmcnt(7)
	v_fmac_f32_e32 v88, v30, v130
	v_fmac_f32_e32 v90, v31, v131
	v_fmac_f32_e32 v88, v28, v132
	v_fmac_f32_e32 v90, v29, v133
	ds_read_b128 v[130:133], v143 offset:13632
	s_waitcnt lgkmcnt(7)
	v_fmac_f32_e32 v88, v26, v134
	v_fmac_f32_e32 v90, v27, v135
	v_fmac_f32_e32 v88, v24, v136
	v_fmac_f32_e32 v90, v25, v137
	ds_read_b128 v[134:137], v143 offset:13648
	s_waitcnt lgkmcnt(7)
	v_fmac_f32_e32 v88, v22, v146
	v_fmac_f32_e32 v90, v23, v147
	v_fmac_f32_e32 v88, v20, v148
	v_fmac_f32_e32 v90, v21, v149
	ds_read_b128 v[146:149], v143 offset:13664
	s_waitcnt lgkmcnt(7)
	v_fmac_f32_e32 v88, v18, v150
	v_fmac_f32_e32 v90, v19, v151
	v_fmac_f32_e32 v88, v16, v152
	v_fmac_f32_e32 v90, v17, v153
	v_add_f32_e32 v84, v88, v90
	v_sub_f32_e32 v14, v14, v84
	ds_read_b128 v[150:153], v143 offset:13680
	s_waitcnt lgkmcnt(7)
	v_fma_f32 v88, v4, v114, 0
	v_fma_f32 v90, v5, v115, 0
	v_fmac_f32_e32 v88, v80, v116
	v_fmac_f32_e32 v90, v81, v117
	ds_read_b128 v[114:117], v143 offset:13696
	s_waitcnt lgkmcnt(7)
	v_fmac_f32_e32 v88, v82, v118
	v_fmac_f32_e32 v90, v83, v119
	v_fmac_f32_e32 v88, v60, v120
	v_fmac_f32_e32 v90, v61, v121
	ds_read_b128 v[118:121], v143 offset:13712
	s_waitcnt lgkmcnt(7)
	v_fmac_f32_e32 v88, v58, v122
	v_fmac_f32_e32 v90, v59, v123
	v_fmac_f32_e32 v88, v56, v124
	v_fmac_f32_e32 v90, v57, v125
	ds_read_b128 v[122:125], v143 offset:13728
	s_waitcnt lgkmcnt(7)
	v_fmac_f32_e32 v88, v54, v126
	v_fmac_f32_e32 v90, v55, v127
	v_fmac_f32_e32 v88, v52, v128
	v_fmac_f32_e32 v90, v53, v129
	ds_read_b128 v[126:129], v143 offset:13744
	s_waitcnt lgkmcnt(7)
	v_fmac_f32_e32 v88, v50, v130
	v_fmac_f32_e32 v90, v51, v131
	v_fmac_f32_e32 v88, v48, v132
	v_fmac_f32_e32 v90, v49, v133
	ds_read_b128 v[130:133], v143 offset:13760
	s_waitcnt lgkmcnt(7)
	v_fmac_f32_e32 v88, v46, v134
	v_fmac_f32_e32 v90, v47, v135
	v_fmac_f32_e32 v88, v44, v136
	v_fmac_f32_e32 v90, v45, v137
	ds_read_b32 v134, v143 offset:13776
	s_waitcnt lgkmcnt(7)
	v_fmac_f32_e32 v88, v42, v146
	v_fmac_f32_e32 v90, v43, v147
	v_fmac_f32_e32 v88, v40, v148
	v_fmac_f32_e32 v90, v41, v149
	ds_read_b128 v[146:149], v143 offset:13824
	s_waitcnt lgkmcnt(7)
	v_fmac_f32_e32 v88, v38, v150
	v_fmac_f32_e32 v90, v39, v151
	v_fmac_f32_e32 v88, v36, v152
	v_fmac_f32_e32 v90, v37, v153
	ds_read_b128 v[150:153], v143 offset:13840
	s_waitcnt lgkmcnt(7)
	v_fmac_f32_e32 v88, v34, v114
	v_fmac_f32_e32 v90, v35, v115
	v_fmac_f32_e32 v88, v32, v116
	v_fmac_f32_e32 v90, v33, v117
	ds_read_b128 v[114:117], v143 offset:13856
	s_waitcnt lgkmcnt(7)
	v_fmac_f32_e32 v88, v30, v118
	v_fmac_f32_e32 v90, v31, v119
	v_fmac_f32_e32 v88, v28, v120
	v_fmac_f32_e32 v90, v29, v121
	ds_read_b128 v[118:121], v143 offset:13872
	s_waitcnt lgkmcnt(7)
	v_fmac_f32_e32 v88, v26, v122
	v_fmac_f32_e32 v90, v27, v123
	v_fmac_f32_e32 v88, v24, v124
	v_fmac_f32_e32 v90, v25, v125
	ds_read_b128 v[122:125], v143 offset:13888
	s_waitcnt lgkmcnt(7)
	v_fmac_f32_e32 v88, v22, v126
	v_fmac_f32_e32 v90, v23, v127
	v_fmac_f32_e32 v88, v20, v128
	v_fmac_f32_e32 v90, v21, v129
	ds_read_b128 v[126:129], v143 offset:13904
	s_waitcnt lgkmcnt(7)
	v_fmac_f32_e32 v88, v18, v130
	v_fmac_f32_e32 v90, v19, v131
	v_fmac_f32_e32 v88, v16, v132
	v_fmac_f32_e32 v90, v17, v133
	ds_read_b128 v[130:133], v143 offset:13920
	s_waitcnt lgkmcnt(7)
	v_fmac_f32_e32 v88, v14, v134
	v_add_f32_e32 v84, v90, v88
	v_sub_f32_e32 v15, v15, v84
	ds_read_b128 v[134:137], v143 offset:13936
	s_waitcnt lgkmcnt(7)
	v_fma_f32 v88, v4, v146, 0
	v_fma_f32 v90, v5, v147, 0
	v_fmac_f32_e32 v88, v80, v148
	v_fmac_f32_e32 v90, v81, v149
	ds_read_b128 v[146:149], v143 offset:13952
	s_waitcnt lgkmcnt(7)
	v_fmac_f32_e32 v88, v82, v150
	v_fmac_f32_e32 v90, v83, v151
	v_fmac_f32_e32 v88, v60, v152
	v_fmac_f32_e32 v90, v61, v153
	ds_read_b128 v[150:153], v143 offset:13968
	s_waitcnt lgkmcnt(7)
	v_fmac_f32_e32 v88, v58, v114
	v_fmac_f32_e32 v90, v59, v115
	v_fmac_f32_e32 v88, v56, v116
	v_fmac_f32_e32 v90, v57, v117
	ds_read_b128 v[114:117], v143 offset:13984
	s_waitcnt lgkmcnt(7)
	v_fmac_f32_e32 v88, v54, v118
	v_fmac_f32_e32 v90, v55, v119
	v_fmac_f32_e32 v88, v52, v120
	v_fmac_f32_e32 v90, v53, v121
	ds_read_b128 v[118:121], v143 offset:14000
	s_waitcnt lgkmcnt(7)
	v_fmac_f32_e32 v88, v50, v122
	v_fmac_f32_e32 v90, v51, v123
	v_fmac_f32_e32 v88, v48, v124
	v_fmac_f32_e32 v90, v49, v125
	ds_read_b128 v[122:125], v143 offset:14016
	s_waitcnt lgkmcnt(7)
	v_fmac_f32_e32 v88, v46, v126
	v_fmac_f32_e32 v90, v47, v127
	v_fmac_f32_e32 v88, v44, v128
	v_fmac_f32_e32 v90, v45, v129
	ds_read_b64 v[126:127], v143 offset:14032
	s_waitcnt lgkmcnt(7)
	v_fmac_f32_e32 v88, v42, v130
	v_fmac_f32_e32 v90, v43, v131
	v_fmac_f32_e32 v88, v40, v132
	v_fmac_f32_e32 v90, v41, v133
	ds_read_b128 v[130:133], v143 offset:14080
	s_waitcnt lgkmcnt(7)
	v_fmac_f32_e32 v88, v38, v134
	v_fmac_f32_e32 v90, v39, v135
	v_fmac_f32_e32 v88, v36, v136
	v_fmac_f32_e32 v90, v37, v137
	ds_read_b128 v[134:137], v143 offset:14096
	s_waitcnt lgkmcnt(7)
	v_fmac_f32_e32 v88, v34, v146
	v_fmac_f32_e32 v90, v35, v147
	v_fmac_f32_e32 v88, v32, v148
	v_fmac_f32_e32 v90, v33, v149
	ds_read_b128 v[146:149], v143 offset:14112
	s_waitcnt lgkmcnt(7)
; DI void gdn_g1(const Params& p, int l, int ch, char* smem) {
;     ...
;     for (int cc = 1; cc < 64; ++cc) { float a0 = 0.f, a1 = 0.f;
; #pragma unroll
;       for (int s2 = 0; s2 < cc; ++s2) { if (s2 & 1) a1 += sA[cc * 64 + s2] * sol[s2]; else a0 += sA[cc * 64 + s2] * sol[s2]; }
;       sol[cc] -= a0 + a1; }
	v_fmac_f32_e32 v88, v30, v150
	v_fmac_f32_e32 v90, v31, v151
	v_fmac_f32_e32 v88, v28, v152
	v_fmac_f32_e32 v90, v29, v153
	ds_read_b128 v[150:153], v143 offset:14128
	s_waitcnt lgkmcnt(7)
	v_fmac_f32_e32 v88, v26, v114
	v_fmac_f32_e32 v90, v27, v115
	v_fmac_f32_e32 v88, v24, v116
	v_fmac_f32_e32 v90, v25, v117
	ds_read_b128 v[114:117], v143 offset:14144
	s_waitcnt lgkmcnt(7)
	v_fmac_f32_e32 v88, v22, v118
	v_fmac_f32_e32 v90, v23, v119
	v_fmac_f32_e32 v88, v20, v120
	v_fmac_f32_e32 v90, v21, v121
	ds_read_b128 v[118:121], v143 offset:14160
	s_waitcnt lgkmcnt(7)
	v_fmac_f32_e32 v88, v18, v122
	v_fmac_f32_e32 v90, v19, v123
	v_fmac_f32_e32 v88, v16, v124
	v_fmac_f32_e32 v90, v17, v125
	ds_read_b128 v[122:125], v143 offset:14176
	s_waitcnt lgkmcnt(7)
	v_fmac_f32_e32 v88, v14, v126
	v_fmac_f32_e32 v90, v15, v127
	v_add_f32_e32 v84, v88, v90
	v_sub_f32_e32 v12, v12, v84
	ds_read_b128 v[126:129], v143 offset:14192
	s_waitcnt lgkmcnt(7)
	v_fma_f32 v88, v4, v130, 0
	v_fma_f32 v90, v5, v131, 0
	v_fmac_f32_e32 v88, v80, v132
	v_fmac_f32_e32 v90, v81, v133
	ds_read_b128 v[130:133], v143 offset:14208
	s_waitcnt lgkmcnt(7)
	v_fmac_f32_e32 v88, v82, v134
	v_fmac_f32_e32 v90, v83, v135
	v_fmac_f32_e32 v88, v60, v136
	v_fmac_f32_e32 v90, v61, v137
	ds_read_b128 v[134:137], v143 offset:14224
	s_waitcnt lgkmcnt(7)
	v_fmac_f32_e32 v88, v58, v146
	v_fmac_f32_e32 v90, v59, v147
	v_fmac_f32_e32 v88, v56, v148
	v_fmac_f32_e32 v90, v57, v149
	ds_read_b128 v[146:149], v143 offset:14240
	s_waitcnt lgkmcnt(7)
	v_fmac_f32_e32 v88, v54, v150
	v_fmac_f32_e32 v90, v55, v151
	v_fmac_f32_e32 v88, v52, v152
	v_fmac_f32_e32 v90, v53, v153
	ds_read_b128 v[150:153], v143 offset:14256
	s_waitcnt lgkmcnt(7)
	v_fmac_f32_e32 v88, v50, v114
	v_fmac_f32_e32 v90, v51, v115
	v_fmac_f32_e32 v88, v48, v116
	v_fmac_f32_e32 v90, v49, v117
	ds_read_b128 v[114:117], v143 offset:14272
	s_waitcnt lgkmcnt(7)
	v_fmac_f32_e32 v88, v46, v118
	v_fmac_f32_e32 v90, v47, v119
	v_fmac_f32_e32 v88, v44, v120
	v_fmac_f32_e32 v90, v45, v121
	ds_read_b96 v[118:120], v143 offset:14288
	s_waitcnt lgkmcnt(7)
	v_fmac_f32_e32 v88, v42, v122
	v_fmac_f32_e32 v90, v43, v123
	v_fmac_f32_e32 v88, v40, v124
	v_fmac_f32_e32 v90, v41, v125
	ds_read_b128 v[122:125], v143 offset:14336
	s_waitcnt lgkmcnt(7)
	v_fmac_f32_e32 v88, v38, v126
	v_fmac_f32_e32 v90, v39, v127
	v_fmac_f32_e32 v88, v36, v128
	v_fmac_f32_e32 v90, v37, v129
	ds_read_b128 v[126:129], v143 offset:14352
	s_waitcnt lgkmcnt(7)
	v_fmac_f32_e32 v88, v34, v130
	v_fmac_f32_e32 v90, v35, v131
	v_fmac_f32_e32 v88, v32, v132
	v_fmac_f32_e32 v90, v33, v133
	ds_read_b128 v[130:133], v143 offset:14368
	s_waitcnt lgkmcnt(7)
	v_fmac_f32_e32 v88, v30, v134
	v_fmac_f32_e32 v90, v31, v135
	v_fmac_f32_e32 v88, v28, v136
	v_fmac_f32_e32 v90, v29, v137
	ds_read_b128 v[134:137], v143 offset:14384
	s_waitcnt lgkmcnt(7)
	v_fmac_f32_e32 v88, v26, v146
	v_fmac_f32_e32 v90, v27, v147
	v_fmac_f32_e32 v88, v24, v148
	v_fmac_f32_e32 v90, v25, v149
	ds_read_b128 v[146:149], v143 offset:14400
	s_waitcnt lgkmcnt(7)
	v_fmac_f32_e32 v88, v22, v150
	v_fmac_f32_e32 v90, v23, v151
	v_fmac_f32_e32 v88, v20, v152
	v_fmac_f32_e32 v90, v21, v153
	ds_read_b128 v[150:153], v143 offset:14416
	s_waitcnt lgkmcnt(7)
	v_fmac_f32_e32 v88, v18, v114
	v_fmac_f32_e32 v90, v19, v115
	v_fmac_f32_e32 v88, v16, v116
	v_fmac_f32_e32 v90, v17, v117
	ds_read_b128 v[114:117], v143 offset:14432
	s_waitcnt lgkmcnt(7)
	v_fmac_f32_e32 v88, v14, v118
	v_fmac_f32_e32 v90, v15, v119
	v_fmac_f32_e32 v88, v12, v120
	v_add_f32_e32 v84, v90, v88
	v_sub_f32_e32 v13, v13, v84
	ds_read_b128 v[118:121], v143 offset:14448
	s_waitcnt lgkmcnt(7)
	v_fma_f32 v88, v4, v122, 0
	v_fma_f32 v90, v5, v123, 0
	v_fmac_f32_e32 v88, v80, v124
	v_fmac_f32_e32 v90, v81, v125
	ds_read_b128 v[122:125], v143 offset:14464
	s_waitcnt lgkmcnt(7)
	v_fmac_f32_e32 v88, v82, v126
	v_fmac_f32_e32 v90, v83, v127
	v_fmac_f32_e32 v88, v60, v128
	v_fmac_f32_e32 v90, v61, v129
	ds_read_b128 v[126:129], v143 offset:14480
	s_waitcnt lgkmcnt(7)
	v_fmac_f32_e32 v88, v58, v130
	v_fmac_f32_e32 v90, v59, v131
	v_fmac_f32_e32 v88, v56, v132
	v_fmac_f32_e32 v90, v57, v133
	ds_read_b128 v[130:133], v143 offset:14496
	s_waitcnt lgkmcnt(7)
	v_fmac_f32_e32 v88, v54, v134
	v_fmac_f32_e32 v90, v55, v135
	v_fmac_f32_e32 v88, v52, v136
	v_fmac_f32_e32 v90, v53, v137
	ds_read_b128 v[134:137], v143 offset:14512
	s_waitcnt lgkmcnt(7)
	v_fmac_f32_e32 v88, v50, v146
	v_fmac_f32_e32 v90, v51, v147
	v_fmac_f32_e32 v88, v48, v148
	v_fmac_f32_e32 v90, v49, v149
	ds_read_b128 v[146:149], v143 offset:14528
	s_waitcnt lgkmcnt(7)
	v_fmac_f32_e32 v88, v46, v150
	v_fmac_f32_e32 v90, v47, v151
	v_fmac_f32_e32 v88, v44, v152
	v_fmac_f32_e32 v90, v45, v153
	ds_read_b128 v[150:153], v143 offset:14544
	s_waitcnt lgkmcnt(7)
	v_fmac_f32_e32 v88, v42, v114
	v_fmac_f32_e32 v90, v43, v115
	v_fmac_f32_e32 v88, v40, v116
	v_fmac_f32_e32 v90, v41, v117
	ds_read_b128 v[114:117], v143 offset:14592
	s_waitcnt lgkmcnt(7)
	v_fmac_f32_e32 v88, v38, v118
	v_fmac_f32_e32 v90, v39, v119
	v_fmac_f32_e32 v88, v36, v120
	v_fmac_f32_e32 v90, v37, v121
	ds_read_b128 v[118:121], v143 offset:14608
	s_waitcnt lgkmcnt(7)
	v_fmac_f32_e32 v88, v34, v122
	v_fmac_f32_e32 v90, v35, v123
	v_fmac_f32_e32 v88, v32, v124
	v_fmac_f32_e32 v90, v33, v125
	ds_read_b128 v[122:125], v143 offset:14624
	s_waitcnt lgkmcnt(7)
	v_fmac_f32_e32 v88, v30, v126
	v_fmac_f32_e32 v90, v31, v127
	v_fmac_f32_e32 v88, v28, v128
	v_fmac_f32_e32 v90, v29, v129
	ds_read_b128 v[126:129], v143 offset:14640
	s_waitcnt lgkmcnt(7)
	v_fmac_f32_e32 v88, v26, v130
	v_fmac_f32_e32 v90, v27, v131
	v_fmac_f32_e32 v88, v24, v132
	v_fmac_f32_e32 v90, v25, v133
	ds_read_b128 v[130:133], v143 offset:14656
	s_waitcnt lgkmcnt(7)
; DI void gdn_g1(const Params& p, int l, int ch, char* smem) {
;     ...
;     for (int cc = 1; cc < 64; ++cc) { float a0 = 0.f, a1 = 0.f;
; #pragma unroll
;       for (int s2 = 0; s2 < cc; ++s2) { if (s2 & 1) a1 += sA[cc * 64 + s2] * sol[s2]; else a0 += sA[cc * 64 + s2] * sol[s2]; }
;       sol[cc] -= a0 + a1; }
	v_fmac_f32_e32 v88, v22, v134
	v_fmac_f32_e32 v90, v23, v135
	v_fmac_f32_e32 v88, v20, v136
	v_fmac_f32_e32 v90, v21, v137
	ds_read_b128 v[134:137], v143 offset:14672
	s_waitcnt lgkmcnt(7)
	v_fmac_f32_e32 v88, v18, v146
	v_fmac_f32_e32 v90, v19, v147
	v_fmac_f32_e32 v88, v16, v148
	v_fmac_f32_e32 v90, v17, v149
	ds_read_b128 v[146:149], v143 offset:14688
	s_waitcnt lgkmcnt(7)
	v_fmac_f32_e32 v88, v14, v150
	v_fmac_f32_e32 v90, v15, v151
	v_fmac_f32_e32 v88, v12, v152
	v_fmac_f32_e32 v90, v13, v153
	v_add_f32_e32 v84, v88, v90
	v_sub_f32_e32 v10, v10, v84
	ds_read_b128 v[150:153], v143 offset:14704
	s_waitcnt lgkmcnt(7)
	v_fma_f32 v88, v4, v114, 0
	v_fma_f32 v90, v5, v115, 0
	v_fmac_f32_e32 v88, v80, v116
	v_fmac_f32_e32 v90, v81, v117
	ds_read_b128 v[114:117], v143 offset:14720
	s_waitcnt lgkmcnt(7)
	v_fmac_f32_e32 v88, v82, v118
	v_fmac_f32_e32 v90, v83, v119
	v_fmac_f32_e32 v88, v60, v120
	v_fmac_f32_e32 v90, v61, v121
	ds_read_b128 v[118:121], v143 offset:14736
	s_waitcnt lgkmcnt(7)
	v_fmac_f32_e32 v88, v58, v122
	v_fmac_f32_e32 v90, v59, v123
	v_fmac_f32_e32 v88, v56, v124
	v_fmac_f32_e32 v90, v57, v125
	ds_read_b128 v[122:125], v143 offset:14752
	s_waitcnt lgkmcnt(7)
	v_fmac_f32_e32 v88, v54, v126
	v_fmac_f32_e32 v90, v55, v127
	v_fmac_f32_e32 v88, v52, v128
	v_fmac_f32_e32 v90, v53, v129
	ds_read_b128 v[126:129], v143 offset:14768
	s_waitcnt lgkmcnt(7)
	v_fmac_f32_e32 v88, v50, v130
	v_fmac_f32_e32 v90, v51, v131
	v_fmac_f32_e32 v88, v48, v132
	v_fmac_f32_e32 v90, v49, v133
	ds_read_b128 v[130:133], v143 offset:14784
	s_waitcnt lgkmcnt(7)
	v_fmac_f32_e32 v88, v46, v134
	v_fmac_f32_e32 v90, v47, v135
	v_fmac_f32_e32 v88, v44, v136
	v_fmac_f32_e32 v90, v45, v137
	ds_read_b128 v[134:137], v143 offset:14800
	s_waitcnt lgkmcnt(7)
	v_fmac_f32_e32 v88, v42, v146
	v_fmac_f32_e32 v90, v43, v147
	v_fmac_f32_e32 v88, v40, v148
	v_fmac_f32_e32 v90, v41, v149
	ds_read_b32 v146, v143 offset:14816
	s_waitcnt lgkmcnt(7)
	v_fmac_f32_e32 v88, v38, v150
	v_fmac_f32_e32 v90, v39, v151
	v_fmac_f32_e32 v88, v36, v152
	v_fmac_f32_e32 v90, v37, v153
	ds_read_b128 v[150:153], v143 offset:14848
	s_waitcnt lgkmcnt(7)
	v_fmac_f32_e32 v88, v34, v114
	v_fmac_f32_e32 v90, v35, v115
	v_fmac_f32_e32 v88, v32, v116
	v_fmac_f32_e32 v90, v33, v117
	ds_read_b128 v[114:117], v143 offset:14864
	s_waitcnt lgkmcnt(7)
	v_fmac_f32_e32 v88, v30, v118
	v_fmac_f32_e32 v90, v31, v119
	v_fmac_f32_e32 v88, v28, v120
	v_fmac_f32_e32 v90, v29, v121
	ds_read_b128 v[118:121], v143 offset:14880
	s_waitcnt lgkmcnt(7)
	v_fmac_f32_e32 v88, v26, v122
	v_fmac_f32_e32 v90, v27, v123
	v_fmac_f32_e32 v88, v24, v124
	v_fmac_f32_e32 v90, v25, v125
	ds_read_b128 v[122:125], v143 offset:14896
	s_waitcnt lgkmcnt(7)
	v_fmac_f32_e32 v88, v22, v126
	v_fmac_f32_e32 v90, v23, v127
	v_fmac_f32_e32 v88, v20, v128
	v_fmac_f32_e32 v90, v21, v129
	ds_read_b128 v[126:129], v143 offset:14912
	s_waitcnt lgkmcnt(7)
	v_fmac_f32_e32 v88, v18, v130
	v_fmac_f32_e32 v90, v19, v131
	v_fmac_f32_e32 v88, v16, v132
	v_fmac_f32_e32 v90, v17, v133
	ds_read_b128 v[130:133], v143 offset:14928
	s_waitcnt lgkmcnt(7)
	v_fmac_f32_e32 v88, v14, v134
	v_fmac_f32_e32 v90, v15, v135
	v_fmac_f32_e32 v88, v12, v136
	v_fmac_f32_e32 v90, v13, v137
	ds_read_b128 v[134:137], v143 offset:14944
	s_waitcnt lgkmcnt(7)
	v_fmac_f32_e32 v88, v10, v146
	v_add_f32_e32 v84, v90, v88
	v_sub_f32_e32 v11, v11, v84
	ds_read_b128 v[146:149], v143 offset:14960
	s_waitcnt lgkmcnt(7)
	v_fma_f32 v88, v4, v150, 0
	v_fma_f32 v90, v5, v151, 0
	v_fmac_f32_e32 v88, v80, v152
	v_fmac_f32_e32 v90, v81, v153
	ds_read_b128 v[150:153], v143 offset:14976
	s_waitcnt lgkmcnt(7)
	v_fmac_f32_e32 v88, v82, v114
	v_fmac_f32_e32 v90, v83, v115
	v_fmac_f32_e32 v88, v60, v116
	v_fmac_f32_e32 v90, v61, v117
	ds_read_b128 v[114:117], v143 offset:14992
	s_waitcnt lgkmcnt(7)
	v_fmac_f32_e32 v88, v58, v118
	v_fmac_f32_e32 v90, v59, v119
	v_fmac_f32_e32 v88, v56, v120
	v_fmac_f32_e32 v90, v57, v121
	ds_read_b128 v[118:121], v143 offset:15008
	s_waitcnt lgkmcnt(7)
	v_fmac_f32_e32 v88, v54, v122
	v_fmac_f32_e32 v90, v55, v123
	v_fmac_f32_e32 v88, v52, v124
	v_fmac_f32_e32 v90, v53, v125
	ds_read_b128 v[122:125], v143 offset:15024
	s_waitcnt lgkmcnt(7)
	v_fmac_f32_e32 v88, v50, v126
	v_fmac_f32_e32 v90, v51, v127
	v_fmac_f32_e32 v88, v48, v128
	v_fmac_f32_e32 v90, v49, v129
	ds_read_b128 v[126:129], v143 offset:15040
	s_waitcnt lgkmcnt(7)
	v_fmac_f32_e32 v88, v46, v130
	v_fmac_f32_e32 v90, v47, v131
	v_fmac_f32_e32 v88, v44, v132
	v_fmac_f32_e32 v90, v45, v133
	ds_read_b128 v[130:133], v143 offset:15056
	s_waitcnt lgkmcnt(7)
	v_fmac_f32_e32 v88, v42, v134
	v_fmac_f32_e32 v90, v43, v135
	v_fmac_f32_e32 v88, v40, v136
	v_fmac_f32_e32 v90, v41, v137
	ds_read_b64 v[134:135], v143 offset:15072
	s_waitcnt lgkmcnt(7)
	v_fmac_f32_e32 v88, v38, v146
	v_fmac_f32_e32 v90, v39, v147
	v_fmac_f32_e32 v88, v36, v148
	v_fmac_f32_e32 v90, v37, v149
	ds_read_b128 v[146:149], v143 offset:15104
	s_waitcnt lgkmcnt(7)
	v_fmac_f32_e32 v88, v34, v150
	v_fmac_f32_e32 v90, v35, v151
	v_fmac_f32_e32 v88, v32, v152
	v_fmac_f32_e32 v90, v33, v153
	ds_read_b128 v[150:153], v143 offset:15120
	s_waitcnt lgkmcnt(7)
	v_fmac_f32_e32 v88, v30, v114
	v_fmac_f32_e32 v90, v31, v115
	v_fmac_f32_e32 v88, v28, v116
	v_fmac_f32_e32 v90, v29, v117
	ds_read_b128 v[114:117], v143 offset:15136
	s_waitcnt lgkmcnt(7)
	v_fmac_f32_e32 v88, v26, v118
	v_fmac_f32_e32 v90, v27, v119
	v_fmac_f32_e32 v88, v24, v120
	v_fmac_f32_e32 v90, v25, v121
	ds_read_b128 v[118:121], v143 offset:15152
	s_waitcnt lgkmcnt(7)
	v_fmac_f32_e32 v88, v22, v122
	v_fmac_f32_e32 v90, v23, v123
	v_fmac_f32_e32 v88, v20, v124
	v_fmac_f32_e32 v90, v21, v125
	ds_read_b128 v[122:125], v143 offset:15168
	s_waitcnt lgkmcnt(7)
; DI void gdn_g1(const Params& p, int l, int ch, char* smem) {
;     ...
;     for (int cc = 1; cc < 64; ++cc) { float a0 = 0.f, a1 = 0.f;
; #pragma unroll
;       for (int s2 = 0; s2 < cc; ++s2) { if (s2 & 1) a1 += sA[cc * 64 + s2] * sol[s2]; else a0 += sA[cc * 64 + s2] * sol[s2]; }
;       sol[cc] -= a0 + a1; }
	v_fmac_f32_e32 v88, v18, v126
	v_fmac_f32_e32 v90, v19, v127
	v_fmac_f32_e32 v88, v16, v128
	v_fmac_f32_e32 v90, v17, v129
	ds_read_b128 v[126:129], v143 offset:15184
	s_waitcnt lgkmcnt(7)
	v_fmac_f32_e32 v88, v14, v130
	v_fmac_f32_e32 v90, v15, v131
	v_fmac_f32_e32 v88, v12, v132
	v_fmac_f32_e32 v90, v13, v133
	ds_read_b128 v[130:133], v143 offset:15200
	s_waitcnt lgkmcnt(7)
	v_fmac_f32_e32 v88, v10, v134
	v_fmac_f32_e32 v90, v11, v135
	v_add_f32_e32 v84, v88, v90
	v_sub_f32_e32 v8, v8, v84
	ds_read_b128 v[134:137], v143 offset:15216
	s_waitcnt lgkmcnt(7)
	v_fma_f32 v88, v4, v146, 0
	v_fma_f32 v90, v5, v147, 0
	v_fmac_f32_e32 v88, v80, v148
	v_fmac_f32_e32 v90, v81, v149
	ds_read_b128 v[146:149], v143 offset:15232
	s_waitcnt lgkmcnt(7)
	v_fmac_f32_e32 v88, v82, v150
	v_fmac_f32_e32 v90, v83, v151
	v_fmac_f32_e32 v88, v60, v152
	v_fmac_f32_e32 v90, v61, v153
	ds_read_b128 v[150:153], v143 offset:15248
	s_waitcnt lgkmcnt(7)
	v_fmac_f32_e32 v88, v58, v114
	v_fmac_f32_e32 v90, v59, v115
	v_fmac_f32_e32 v88, v56, v116
	v_fmac_f32_e32 v90, v57, v117
	ds_read_b128 v[114:117], v143 offset:15264
	s_waitcnt lgkmcnt(7)
	v_fmac_f32_e32 v88, v54, v118
	v_fmac_f32_e32 v90, v55, v119
	v_fmac_f32_e32 v88, v52, v120
	v_fmac_f32_e32 v90, v53, v121
	ds_read_b128 v[118:121], v143 offset:15280
	s_waitcnt lgkmcnt(7)
	v_fmac_f32_e32 v88, v50, v122
	v_fmac_f32_e32 v90, v51, v123
	v_fmac_f32_e32 v88, v48, v124
	v_fmac_f32_e32 v90, v49, v125
	ds_read_b128 v[122:125], v143 offset:15296
	s_waitcnt lgkmcnt(7)
	v_fmac_f32_e32 v88, v46, v126
	v_fmac_f32_e32 v90, v47, v127
	v_fmac_f32_e32 v88, v44, v128
	v_fmac_f32_e32 v90, v45, v129
	ds_read_b128 v[126:129], v143 offset:15312
	s_waitcnt lgkmcnt(7)
	v_fmac_f32_e32 v88, v42, v130
	v_fmac_f32_e32 v90, v43, v131
	v_fmac_f32_e32 v88, v40, v132
	v_fmac_f32_e32 v90, v41, v133
	ds_read_b96 v[130:132], v143 offset:15328
	s_waitcnt lgkmcnt(7)
	v_fmac_f32_e32 v88, v38, v134
	v_fmac_f32_e32 v90, v39, v135
	v_fmac_f32_e32 v88, v36, v136
	v_fmac_f32_e32 v90, v37, v137
	ds_read_b128 v[134:137], v143 offset:15360
	s_waitcnt lgkmcnt(7)
	v_fmac_f32_e32 v88, v34, v146
	v_fmac_f32_e32 v90, v35, v147
	v_fmac_f32_e32 v88, v32, v148
	v_fmac_f32_e32 v90, v33, v149
	ds_read_b128 v[146:149], v143 offset:15376
	s_waitcnt lgkmcnt(7)
	v_fmac_f32_e32 v88, v30, v150
	v_fmac_f32_e32 v90, v31, v151
	v_fmac_f32_e32 v88, v28, v152
	v_fmac_f32_e32 v90, v29, v153
	ds_read_b128 v[150:153], v143 offset:15392
	s_waitcnt lgkmcnt(7)
	v_fmac_f32_e32 v88, v26, v114
	v_fmac_f32_e32 v90, v27, v115
	v_fmac_f32_e32 v88, v24, v116
	v_fmac_f32_e32 v90, v25, v117
	ds_read_b128 v[114:117], v143 offset:15408
	s_waitcnt lgkmcnt(7)
	v_fmac_f32_e32 v88, v22, v118
	v_fmac_f32_e32 v90, v23, v119
	v_fmac_f32_e32 v88, v20, v120
	v_fmac_f32_e32 v90, v21, v121
	ds_read_b128 v[118:121], v143 offset:15424
	s_waitcnt lgkmcnt(7)
	v_fmac_f32_e32 v88, v18, v122
	v_fmac_f32_e32 v90, v19, v123
	v_fmac_f32_e32 v88, v16, v124
	v_fmac_f32_e32 v90, v17, v125
	ds_read_b128 v[122:125], v143 offset:15440
	s_waitcnt lgkmcnt(7)
	v_fmac_f32_e32 v88, v14, v126
	v_fmac_f32_e32 v90, v15, v127
	v_fmac_f32_e32 v88, v12, v128
	v_fmac_f32_e32 v90, v13, v129
	ds_read_b128 v[126:129], v143 offset:15456
	s_waitcnt lgkmcnt(7)
	v_fmac_f32_e32 v88, v10, v130
	v_fmac_f32_e32 v90, v11, v131
	v_fmac_f32_e32 v88, v8, v132
	v_add_f32_e32 v84, v90, v88
	v_sub_f32_e32 v9, v9, v84
	ds_read_b128 v[130:133], v143 offset:15472
	s_waitcnt lgkmcnt(7)
	v_fma_f32 v88, v4, v134, 0
	v_fma_f32 v90, v5, v135, 0
	v_fmac_f32_e32 v88, v80, v136
	v_fmac_f32_e32 v90, v81, v137
	ds_read_b128 v[134:137], v143 offset:15488
	s_waitcnt lgkmcnt(7)
	v_fmac_f32_e32 v88, v82, v146
	v_fmac_f32_e32 v90, v83, v147
	v_fmac_f32_e32 v88, v60, v148
	v_fmac_f32_e32 v90, v61, v149
	ds_read_b128 v[146:149], v143 offset:15504
	s_waitcnt lgkmcnt(7)
	v_fmac_f32_e32 v88, v58, v150
	v_fmac_f32_e32 v90, v59, v151
	v_fmac_f32_e32 v88, v56, v152
	v_fmac_f32_e32 v90, v57, v153
	ds_read_b128 v[150:153], v143 offset:15520
	s_waitcnt lgkmcnt(7)
	v_fmac_f32_e32 v88, v54, v114
	v_fmac_f32_e32 v90, v55, v115
	v_fmac_f32_e32 v88, v52, v116
	v_fmac_f32_e32 v90, v53, v117
	ds_read_b128 v[114:117], v143 offset:15536
	s_waitcnt lgkmcnt(7)
	v_fmac_f32_e32 v88, v50, v118
	v_fmac_f32_e32 v90, v51, v119
	v_fmac_f32_e32 v88, v48, v120
	v_fmac_f32_e32 v90, v49, v121
	ds_read_b128 v[118:121], v143 offset:15552
	s_waitcnt lgkmcnt(7)
	v_fmac_f32_e32 v88, v46, v122
	v_fmac_f32_e32 v90, v47, v123
	v_fmac_f32_e32 v88, v44, v124
	v_fmac_f32_e32 v90, v45, v125
	ds_read_b128 v[122:125], v143 offset:15568
	s_waitcnt lgkmcnt(7)
	v_fmac_f32_e32 v88, v42, v126
	v_fmac_f32_e32 v90, v43, v127
	v_fmac_f32_e32 v88, v40, v128
	v_fmac_f32_e32 v90, v41, v129
	ds_read_b128 v[126:129], v143 offset:15584
	s_waitcnt lgkmcnt(7)
	v_fmac_f32_e32 v88, v38, v130
	v_fmac_f32_e32 v90, v39, v131
	v_fmac_f32_e32 v88, v36, v132
	v_fmac_f32_e32 v90, v37, v133
	ds_read_b128 v[130:133], v143 offset:15616
	s_waitcnt lgkmcnt(7)
	v_fmac_f32_e32 v88, v34, v134
	v_fmac_f32_e32 v90, v35, v135
	v_fmac_f32_e32 v88, v32, v136
	v_fmac_f32_e32 v90, v33, v137
	ds_read_b128 v[134:137], v143 offset:15632
	s_waitcnt lgkmcnt(7)
	v_fmac_f32_e32 v88, v30, v146
	v_fmac_f32_e32 v90, v31, v147
	v_fmac_f32_e32 v88, v28, v148
	v_fmac_f32_e32 v90, v29, v149
	ds_read_b128 v[146:149], v143 offset:15648
	s_waitcnt lgkmcnt(7)
	v_fmac_f32_e32 v88, v26, v150
	v_fmac_f32_e32 v90, v27, v151
	v_fmac_f32_e32 v88, v24, v152
	v_fmac_f32_e32 v90, v25, v153
	ds_read_b128 v[150:153], v143 offset:15664
	s_waitcnt lgkmcnt(7)
	v_fmac_f32_e32 v88, v22, v114
	v_fmac_f32_e32 v90, v23, v115
	v_fmac_f32_e32 v88, v20, v116
	v_fmac_f32_e32 v90, v21, v117
	ds_read_b128 v[114:117], v143 offset:15680
	s_waitcnt lgkmcnt(7)
; DI void gdn_g1(const Params& p, int l, int ch, char* smem) {
;     ...
;     for (int cc = 1; cc < 64; ++cc) { float a0 = 0.f, a1 = 0.f;
; #pragma unroll
;       for (int s2 = 0; s2 < cc; ++s2) { if (s2 & 1) a1 += sA[cc * 64 + s2] * sol[s2]; else a0 += sA[cc * 64 + s2] * sol[s2]; }
;       sol[cc] -= a0 + a1; }
	v_fmac_f32_e32 v88, v18, v118
	v_fmac_f32_e32 v90, v19, v119
	v_fmac_f32_e32 v88, v16, v120
	v_fmac_f32_e32 v90, v17, v121
	ds_read_b128 v[118:121], v143 offset:15696
	s_waitcnt lgkmcnt(7)
	v_fmac_f32_e32 v88, v14, v122
	v_fmac_f32_e32 v90, v15, v123
	v_fmac_f32_e32 v88, v12, v124
	v_fmac_f32_e32 v90, v13, v125
	ds_read_b128 v[122:125], v143 offset:15712
	s_waitcnt lgkmcnt(7)
	v_fmac_f32_e32 v88, v10, v126
	v_fmac_f32_e32 v90, v11, v127
	v_fmac_f32_e32 v88, v8, v128
	v_fmac_f32_e32 v90, v9, v129
	v_add_f32_e32 v84, v88, v90
	v_sub_f32_e32 v6, v6, v84
	ds_read_b128 v[126:129], v143 offset:15728
	s_waitcnt lgkmcnt(7)
	v_fma_f32 v88, v4, v130, 0
	v_fma_f32 v90, v5, v131, 0
	v_fmac_f32_e32 v88, v80, v132
	v_fmac_f32_e32 v90, v81, v133
	ds_read_b128 v[130:133], v143 offset:15744
	s_waitcnt lgkmcnt(7)
	v_fmac_f32_e32 v88, v82, v134
	v_fmac_f32_e32 v90, v83, v135
	v_fmac_f32_e32 v88, v60, v136
	v_fmac_f32_e32 v90, v61, v137
	ds_read_b128 v[134:137], v143 offset:15760
	s_waitcnt lgkmcnt(7)
	v_fmac_f32_e32 v88, v58, v146
	v_fmac_f32_e32 v90, v59, v147
	v_fmac_f32_e32 v88, v56, v148
	v_fmac_f32_e32 v90, v57, v149
	ds_read_b128 v[146:149], v143 offset:15776
	s_waitcnt lgkmcnt(7)
	v_fmac_f32_e32 v88, v54, v150
	v_fmac_f32_e32 v90, v55, v151
	v_fmac_f32_e32 v88, v52, v152
	v_fmac_f32_e32 v90, v53, v153
	ds_read_b128 v[150:153], v143 offset:15792
	s_waitcnt lgkmcnt(7)
	v_fmac_f32_e32 v88, v50, v114
	v_fmac_f32_e32 v90, v51, v115
	v_fmac_f32_e32 v88, v48, v116
	v_fmac_f32_e32 v90, v49, v117
	ds_read_b128 v[114:117], v143 offset:15808
	s_waitcnt lgkmcnt(7)
	v_fmac_f32_e32 v88, v46, v118
	v_fmac_f32_e32 v90, v47, v119
	v_fmac_f32_e32 v88, v44, v120
	v_fmac_f32_e32 v90, v45, v121
	ds_read_b128 v[118:121], v143 offset:15824
	s_waitcnt lgkmcnt(7)
	v_fmac_f32_e32 v88, v42, v122
	v_fmac_f32_e32 v90, v43, v123
	v_fmac_f32_e32 v88, v40, v124
	v_fmac_f32_e32 v90, v41, v125
	ds_read_b128 v[122:125], v143 offset:15840
	s_waitcnt lgkmcnt(7)
	v_fmac_f32_e32 v88, v38, v126
	v_fmac_f32_e32 v90, v39, v127
	v_fmac_f32_e32 v88, v36, v128
	v_fmac_f32_e32 v90, v37, v129
	ds_read_b32 v126, v143 offset:15856
	s_waitcnt lgkmcnt(7)
	v_fmac_f32_e32 v88, v34, v130
	v_fmac_f32_e32 v90, v35, v131
	v_fmac_f32_e32 v88, v32, v132
	v_fmac_f32_e32 v90, v33, v133
	ds_read_b128 v[130:133], v143 offset:15872
	s_waitcnt lgkmcnt(7)
	v_fmac_f32_e32 v88, v30, v134
	v_fmac_f32_e32 v90, v31, v135
	v_fmac_f32_e32 v88, v28, v136
	v_fmac_f32_e32 v90, v29, v137
	ds_read_b128 v[134:137], v143 offset:15888
	s_waitcnt lgkmcnt(7)
	v_fmac_f32_e32 v88, v26, v146
	v_fmac_f32_e32 v90, v27, v147
	v_fmac_f32_e32 v88, v24, v148
	v_fmac_f32_e32 v90, v25, v149
	ds_read_b128 v[146:149], v143 offset:15904
	s_waitcnt lgkmcnt(7)
	v_fmac_f32_e32 v88, v22, v150
	v_fmac_f32_e32 v90, v23, v151
	v_fmac_f32_e32 v88, v20, v152
	v_fmac_f32_e32 v90, v21, v153
	ds_read_b128 v[150:153], v143 offset:15920
	s_waitcnt lgkmcnt(7)
	v_fmac_f32_e32 v88, v18, v114
	v_fmac_f32_e32 v90, v19, v115
	v_fmac_f32_e32 v88, v16, v116
	v_fmac_f32_e32 v90, v17, v117
	ds_read_b128 v[114:117], v143 offset:15936
	s_waitcnt lgkmcnt(7)
	v_fmac_f32_e32 v88, v14, v118
	v_fmac_f32_e32 v90, v15, v119
	v_fmac_f32_e32 v88, v12, v120
	v_fmac_f32_e32 v90, v13, v121
	ds_read_b128 v[118:121], v143 offset:15952
	s_waitcnt lgkmcnt(7)
	v_fmac_f32_e32 v88, v10, v122
	v_fmac_f32_e32 v90, v11, v123
	v_fmac_f32_e32 v88, v8, v124
	v_fmac_f32_e32 v90, v9, v125
	ds_read_b128 v[122:125], v143 offset:15968
	s_waitcnt lgkmcnt(7)
	v_fmac_f32_e32 v88, v6, v126
	v_add_f32_e32 v84, v90, v88
	v_sub_f32_e32 v7, v7, v84
	ds_read_b128 v[126:129], v143 offset:15984
	s_waitcnt lgkmcnt(7)
	v_fma_f32 v88, v4, v130, 0
	v_fma_f32 v90, v5, v131, 0
	v_fmac_f32_e32 v88, v80, v132
	v_fmac_f32_e32 v90, v81, v133
	ds_read_b128 v[130:133], v143 offset:16000
	s_waitcnt lgkmcnt(7)
	v_fmac_f32_e32 v88, v82, v134
	v_fmac_f32_e32 v90, v83, v135
	v_fmac_f32_e32 v88, v60, v136
	v_fmac_f32_e32 v90, v61, v137
	ds_read_b128 v[134:137], v143 offset:16016
	s_waitcnt lgkmcnt(7)
	v_fmac_f32_e32 v88, v58, v146
	v_fmac_f32_e32 v90, v59, v147
	v_fmac_f32_e32 v88, v56, v148
	v_fmac_f32_e32 v90, v57, v149
	ds_read_b128 v[146:149], v143 offset:16032
	s_waitcnt lgkmcnt(7)
	v_fmac_f32_e32 v88, v54, v150
	v_fmac_f32_e32 v90, v55, v151
	v_fmac_f32_e32 v88, v52, v152
	v_fmac_f32_e32 v90, v53, v153
	ds_read_b128 v[150:153], v143 offset:16048
	s_waitcnt lgkmcnt(7)
	v_fmac_f32_e32 v88, v50, v114
	v_fmac_f32_e32 v90, v51, v115
	v_fmac_f32_e32 v88, v48, v116
	v_fmac_f32_e32 v90, v49, v117
	ds_read_b128 v[114:117], v143 offset:16064
	s_waitcnt lgkmcnt(7)
	v_fmac_f32_e32 v88, v46, v118
	v_fmac_f32_e32 v90, v47, v119
	v_fmac_f32_e32 v88, v44, v120
	v_fmac_f32_e32 v90, v45, v121
	ds_read_b128 v[118:121], v143 offset:16080
	s_waitcnt lgkmcnt(7)
	v_fmac_f32_e32 v88, v42, v122
	v_fmac_f32_e32 v90, v43, v123
	v_fmac_f32_e32 v88, v40, v124
	v_fmac_f32_e32 v90, v41, v125
	ds_read_b128 v[122:125], v143 offset:16096
	s_waitcnt lgkmcnt(7)
	v_fmac_f32_e32 v88, v38, v126
	v_fmac_f32_e32 v90, v39, v127
	v_fmac_f32_e32 v88, v36, v128
	v_fmac_f32_e32 v90, v37, v129
	ds_read_b64 v[126:127], v143 offset:16112
	s_waitcnt lgkmcnt(7)
	v_fmac_f32_e32 v88, v34, v130
	v_fmac_f32_e32 v90, v35, v131
	v_fmac_f32_e32 v88, v32, v132
	v_fmac_f32_e32 v90, v33, v133
	ds_read_b128 v[130:133], v143 offset:16128
	s_waitcnt lgkmcnt(7)
	v_fmac_f32_e32 v88, v30, v134
	v_fmac_f32_e32 v90, v31, v135
	v_fmac_f32_e32 v88, v28, v136
	v_fmac_f32_e32 v90, v29, v137
	ds_read_b128 v[134:137], v143 offset:16144
	s_waitcnt lgkmcnt(7)
	v_fmac_f32_e32 v88, v26, v146
	v_fmac_f32_e32 v90, v27, v147
	v_fmac_f32_e32 v88, v24, v148
	v_fmac_f32_e32 v90, v25, v149
	ds_read_b128 v[146:149], v143 offset:16160
	s_waitcnt lgkmcnt(7)
; DI void gdn_g1(const Params& p, int l, int ch, char* smem) {
;     ...
;     for (int cc = 1; cc < 64; ++cc) { float a0 = 0.f, a1 = 0.f;
; #pragma unroll
;       for (int s2 = 0; s2 < cc; ++s2) { if (s2 & 1) a1 += sA[cc * 64 + s2] * sol[s2]; else a0 += sA[cc * 64 + s2] * sol[s2]; }
;       sol[cc] -= a0 + a1; }
; #pragma unroll
;     for (int cc = 1; cc < 64; ++cc) sR[cc * 129 + tid] = sol[cc];
	v_fmac_f32_e32 v88, v22, v150
	v_fmac_f32_e32 v90, v23, v151
	v_fmac_f32_e32 v88, v20, v152
	v_fmac_f32_e32 v90, v21, v153
	ds_read_b128 v[150:153], v143 offset:16176
	s_waitcnt lgkmcnt(7)
	v_fmac_f32_e32 v88, v18, v114
	v_fmac_f32_e32 v90, v19, v115
	v_fmac_f32_e32 v88, v16, v116
	v_fmac_f32_e32 v90, v17, v117
	ds_read_b128 v[114:117], v143 offset:16192
	s_waitcnt lgkmcnt(7)
	v_fmac_f32_e32 v88, v14, v118
	v_fmac_f32_e32 v90, v15, v119
	v_fmac_f32_e32 v88, v12, v120
	v_fmac_f32_e32 v90, v13, v121
	ds_read_b128 v[118:121], v143 offset:16208
	s_waitcnt lgkmcnt(7)
	v_fmac_f32_e32 v88, v10, v122
	v_fmac_f32_e32 v90, v11, v123
	v_fmac_f32_e32 v88, v8, v124
	v_fmac_f32_e32 v90, v9, v125
	ds_read_b128 v[122:125], v143 offset:16224
	s_waitcnt lgkmcnt(7)
	v_fmac_f32_e32 v88, v6, v126
	v_fmac_f32_e32 v90, v7, v127
	v_add_f32_e32 v84, v88, v90
	v_sub_f32_e32 v2, v2, v84
	ds_read_b128 v[126:129], v143 offset:16240
	s_waitcnt lgkmcnt(7)
	v_fma_f32 v4, v4, v130, 0
	v_fma_f32 v88, v5, v131, 0
	v_fmac_f32_e32 v4, v80, v132
	v_fmac_f32_e32 v88, v81, v133
	ds_read_b128 v[130:133], v143 offset:16256
	s_waitcnt lgkmcnt(7)
	v_fmac_f32_e32 v4, v82, v134
	v_fmac_f32_e32 v88, v83, v135
	v_fmac_f32_e32 v4, v60, v136
	v_fmac_f32_e32 v88, v61, v137
	ds_read_b128 v[134:137], v143 offset:16272
	s_waitcnt lgkmcnt(7)
	v_fmac_f32_e32 v4, v58, v146
	v_fmac_f32_e32 v88, v59, v147
	v_fmac_f32_e32 v4, v56, v148
	v_fmac_f32_e32 v88, v57, v149
	ds_read_b128 v[146:149], v143 offset:16288
	s_waitcnt lgkmcnt(7)
	v_fmac_f32_e32 v4, v54, v150
	v_fmac_f32_e32 v88, v55, v151
	v_fmac_f32_e32 v4, v52, v152
	v_fmac_f32_e32 v88, v53, v153
	ds_read_b128 v[150:153], v143 offset:16304
	s_waitcnt lgkmcnt(7)
	v_fmac_f32_e32 v4, v50, v114
	v_fmac_f32_e32 v88, v51, v115
	v_fmac_f32_e32 v4, v48, v116
	v_fmac_f32_e32 v88, v49, v117
	ds_read_b128 v[114:117], v143 offset:16320
	s_waitcnt lgkmcnt(7)
	v_fmac_f32_e32 v4, v46, v118
	v_fmac_f32_e32 v88, v47, v119
	v_fmac_f32_e32 v4, v44, v120
	v_fmac_f32_e32 v88, v45, v121
	ds_read_b128 v[118:121], v143 offset:16336
	s_waitcnt lgkmcnt(7)
	v_fmac_f32_e32 v4, v42, v122
	v_fmac_f32_e32 v88, v43, v123
	v_fmac_f32_e32 v4, v40, v124
	v_fmac_f32_e32 v88, v41, v125
	ds_read_b128 v[122:125], v143 offset:16352
	s_waitcnt lgkmcnt(7)
	v_fmac_f32_e32 v4, v38, v126
	v_fmac_f32_e32 v88, v39, v127
	v_fmac_f32_e32 v4, v36, v128
	v_fmac_f32_e32 v88, v37, v129
	ds_read_b96 v[126:128], v143 offset:16368
	s_waitcnt lgkmcnt(7)
	v_fmac_f32_e32 v4, v34, v130
	v_fmac_f32_e32 v88, v35, v131
	v_fmac_f32_e32 v4, v32, v132
	v_fmac_f32_e32 v88, v33, v133
	s_waitcnt lgkmcnt(6)
	v_fmac_f32_e32 v4, v30, v134
	v_fmac_f32_e32 v88, v31, v135
	v_fmac_f32_e32 v4, v28, v136
	v_fmac_f32_e32 v88, v29, v137
	s_waitcnt lgkmcnt(5)
	v_fmac_f32_e32 v4, v26, v146
	v_fmac_f32_e32 v88, v27, v147
	v_fmac_f32_e32 v4, v24, v148
	v_fmac_f32_e32 v88, v25, v149
	s_waitcnt lgkmcnt(4)
	v_fmac_f32_e32 v4, v22, v150
	v_fmac_f32_e32 v88, v23, v151
	v_fmac_f32_e32 v4, v20, v152
	v_fmac_f32_e32 v88, v21, v153
	s_waitcnt lgkmcnt(3)
	v_fmac_f32_e32 v4, v18, v114
	v_fmac_f32_e32 v88, v19, v115
	v_fmac_f32_e32 v4, v16, v116
	v_fmac_f32_e32 v88, v17, v117
	s_waitcnt lgkmcnt(2)
	v_fmac_f32_e32 v4, v14, v118
	v_fmac_f32_e32 v88, v15, v119
	v_fmac_f32_e32 v4, v12, v120
	v_fmac_f32_e32 v88, v13, v121
	s_waitcnt lgkmcnt(1)
	v_fmac_f32_e32 v4, v10, v122
	v_fmac_f32_e32 v88, v11, v123
	v_fmac_f32_e32 v4, v8, v124
	v_fmac_f32_e32 v88, v9, v125
	s_waitcnt lgkmcnt(0)
	v_fmac_f32_e32 v4, v6, v126
	v_fmac_f32_e32 v88, v7, v127
	v_fmac_f32_e32 v4, v2, v128
	v_add_f32_e32 v4, v88, v4
	v_sub_f32_e32 v3, v3, v4
	v_add_u32_e32 v4, 0x4200, v79
	ds_write2_b32 v4, v5, v80 offset0:1 offset1:130
	v_add_u32_e32 v4, 0x4600, v79
	ds_write2_b32 v4, v81, v82 offset0:3 offset1:132
	v_add_u32_e32 v4, 0x4a00, v79
	ds_write2_b32 v4, v83, v60 offset0:5 offset1:134
	v_add_u32_e32 v4, 0x4e00, v79
	ds_write2_b32 v4, v61, v58 offset0:7 offset1:136
	v_add_u32_e32 v4, 0x5200, v79
	ds_write2_b32 v4, v59, v56 offset0:9 offset1:138
	v_add_u32_e32 v4, 0x5600, v79
	ds_write2_b32 v4, v57, v54 offset0:11 offset1:140
	v_add_u32_e32 v4, 0x5a00, v79
	ds_write2_b32 v4, v55, v52 offset0:13 offset1:142
	v_add_u32_e32 v4, 0x5e00, v79
	ds_write2_b32 v4, v53, v50 offset0:15 offset1:144
	v_add_u32_e32 v4, 0x6200, v79
	ds_write2_b32 v4, v51, v48 offset0:17 offset1:146
	v_add_u32_e32 v4, 0x6600, v79
	ds_write2_b32 v4, v49, v46 offset0:19 offset1:148
	v_add_u32_e32 v4, 0x6a00, v79
	ds_write2_b32 v4, v47, v44 offset0:21 offset1:150
	v_add_u32_e32 v4, 0x6e00, v79
	ds_write2_b32 v4, v45, v42 offset0:23 offset1:152
	v_add_u32_e32 v4, 0x7200, v79
	ds_write2_b32 v4, v43, v40 offset0:25 offset1:154
	v_add_u32_e32 v4, 0x7600, v79
	ds_write2_b32 v4, v41, v38 offset0:27 offset1:156
	v_add_u32_e32 v4, 0x7a00, v79
	ds_write2_b32 v4, v39, v36 offset0:29 offset1:158
	v_add_u32_e32 v4, 0x7e00, v79
	ds_write2_b32 v4, v37, v34 offset0:31 offset1:160
	v_add_u32_e32 v4, 0x8200, v79
	ds_write2_b32 v4, v35, v32 offset0:33 offset1:162
	v_add_u32_e32 v4, 0x8600, v79
	ds_write2_b32 v4, v33, v30 offset0:35 offset1:164
	v_add_u32_e32 v4, 0x8a00, v79
	ds_write2_b32 v4, v31, v28 offset0:37 offset1:166
	v_add_u32_e32 v4, 0x8e00, v79
	ds_write2_b32 v4, v29, v26 offset0:39 offset1:168
	v_add_u32_e32 v4, 0x9200, v79
	ds_write2_b32 v4, v27, v24 offset0:41 offset1:170
	v_add_u32_e32 v4, 0x9600, v79
	ds_write2_b32 v4, v25, v22 offset0:43 offset1:172
	v_add_u32_e32 v4, 0x9a00, v79
	ds_write2_b32 v4, v23, v20 offset0:45 offset1:174
	v_add_u32_e32 v4, 0x9e00, v79
	ds_write2_b32 v4, v21, v18 offset0:47 offset1:176
	v_add_u32_e32 v4, 0xa200, v79
	ds_write2_b32 v4, v19, v16 offset0:49 offset1:178
	v_add_u32_e32 v4, 0xa600, v79
	ds_write2_b32 v4, v17, v14 offset0:51 offset1:180
	v_add_u32_e32 v4, 0xaa00, v79
	ds_write2_b32 v4, v15, v12 offset0:53 offset1:182
	v_add_u32_e32 v4, 0xae00, v79
	ds_write2_b32 v4, v13, v10 offset0:55 offset1:184
	v_add_u32_e32 v4, 0xb200, v79
	ds_write2_b32 v4, v11, v8 offset0:57 offset1:186
	v_add_u32_e32 v4, 0xb600, v79
	ds_write2_b32 v4, v9, v6 offset0:59 offset1:188
	v_add_u32_e32 v4, 0xba00, v79
	ds_write2_b32 v4, v7, v2 offset0:61 offset1:190
	ds_write_b32 v79, v3 offset:48892
